# hyena order-1 output written channel-major (8-byte stores, in place over its consumed input row) plus a per-WG LDS transposing pass before the GLU phase; lists gather loop batched; attention exp scale
# speedup vs baseline: 1.0625x; 1.0233x over previous
; __device__ __forceinline__ u16 f2bf(float f) { unsigned r; asm("v_cvt_pk_bf16_f32 %0, %1, %1" : "=v"(r) : "v"(f)); return (u16)r; }
; __device__ __forceinline__ unsigned pack2(float a, float b) { unsigned r; asm("v_cvt_pk_bf16_f32 %0, %1, %2" : "=v"(r) : "v"(a), "v"(b)); return r; }
; __device__ __forceinline__ void hyena_task(const Params& p, int layer, int c, bool isctx, unsigned char* smem) {
;     ...
;       if (tt < 8) {
;         size_t rowoff = (size_t)rowbase + (size_t)bb * Ls;
; #pragma unroll
;         for (int i = 0; i < 8; i++) {
;           int t0 = 16 * (mi0 + i) + 4 * kg;
;           uint2 gq = *(const uint2*)(GT + bb * HY_YS + t0);
;           uint2 yv = *(const uint2*)(YT + bb * HY_YS + t0);
;           float r0 = __uint_as_float(gq.x << 16) * (acc[i][0] + hb * __uint_as_float(yv.x << 16));
;           float r1 = __uint_as_float(gq.x & 0xffff0000u) * (acc[i][1] + hb * __uint_as_float(yv.x & 0xffff0000u));
;           float r2 = __uint_as_float(gq.y << 16) * (acc[i][2] + hb * __uint_as_float(yv.y << 16));
;           float r3 = __uint_as_float(gq.y & 0xffff0000u) * (acc[i][3] + hb * __uint_as_float(yv.y & 0xffff0000u));
;           if (o == 0) {
;             uint2 ov; ov.x = pack2(r0, r1); ov.y = pack2(r2, r3);
;             *(uint2*)(YB + bb * HY_YS + t0) = ov;
;           } else {
;             u16* YS = (u16*)(p.ws + O_YS) + (rowoff + t0) * 1536 + 1024 + c;
;             YS[0] = f2bf(r0); YS[1536] = f2bf(r1); YS[2 * 1536] = f2bf(r2); YS[3 * 1536] = f2bf(r3);
;           }
.Lhy_epi:
	s_mov_b64 s[50:51], exec
	s_cbranch_execz .LBB0_385
	v_or_b32_e32 v24, v113, v116
	v_bfe_u32 v25, v66, 3, 1
	v_lshl_or_b32 v24, v25, 7, v24
	v_lshlrev_b32_e32 v25, 1, v24
	v_add_u32_e32 v27, v57, v25
	v_add_u32_e32 v26, v117, v25
	ds_read_b64 v[36:37], v27
	ds_read_b64 v[34:35], v26
	s_mov_b64 s[4:5], -1
	s_and_b64 vcc, exec, s[40:41]
	s_waitcnt lgkmcnt(0)
	v_lshlrev_b32_e32 v32, 16, v36
	v_lshlrev_b32_e32 v25, 16, v34
	s_waitcnt vmcnt(0)
	v_fma_f32 v32, s100, v32, v52
	v_mul_f32_e32 v32, v32, v25
	v_and_b32_e32 v25, 0xffff0000, v36
	v_and_b32_e32 v33, 0xffff0000, v34
	v_fma_f32 v25, s100, v25, v53
	v_lshlrev_b32_e32 v34, 16, v37
	v_mul_f32_e32 v33, v25, v33
	v_lshlrev_b32_e32 v25, 16, v35
	v_fma_f32 v34, s100, v34, v54
	v_mul_f32_e32 v34, v34, v25
	v_and_b32_e32 v25, 0xffff0000, v35
	v_and_b32_e32 v35, 0xffff0000, v37
	v_fmac_f32_e32 v55, s100, v35
	v_mul_f32_e32 v35, v55, v25
	s_cbranch_vccz .LBB0_391
	v_ashrrev_i32_e32 v25, 31, v24
	v_lshl_add_u64 v[38:39], v[24:25], 0, v[68:69]
	v_lshl_add_u64 v[38:39], v[38:39], 1, v[80:81]
	v_cvt_pk_bf16_f32 v40, v32, v33
	v_cvt_pk_bf16_f32 v41, v34, v35
	global_store_dwordx2 v[38:39], v[40:41], off
	s_mov_b64 s[4:5], 0

; __device__ __forceinline__ u16 f2bf(float f) { unsigned r; asm("v_cvt_pk_bf16_f32 %0, %1, %1" : "=v"(r) : "v"(f)); return (u16)r; }
; __device__ __forceinline__ unsigned pack2(float a, float b) { unsigned r; asm("v_cvt_pk_bf16_f32 %0, %1, %2" : "=v"(r) : "v"(a), "v"(b)); return r; }
; __device__ __forceinline__ void hyena_task(const Params& p, int layer, int c, bool isctx, unsigned char* smem) {
;     ...
;       if (tt < 8) {
;         size_t rowoff = (size_t)rowbase + (size_t)bb * Ls;
; #pragma unroll
;         for (int i = 0; i < 8; i++) {
;           int t0 = 16 * (mi0 + i) + 4 * kg;
;           uint2 gq = *(const uint2*)(GT + bb * HY_YS + t0);
;           uint2 yv = *(const uint2*)(YT + bb * HY_YS + t0);
;           float r0 = __uint_as_float(gq.x << 16) * (acc[i][0] + hb * __uint_as_float(yv.x << 16));
;           float r1 = __uint_as_float(gq.x & 0xffff0000u) * (acc[i][1] + hb * __uint_as_float(yv.x & 0xffff0000u));
;           float r2 = __uint_as_float(gq.y << 16) * (acc[i][2] + hb * __uint_as_float(yv.y << 16));
;           float r3 = __uint_as_float(gq.y & 0xffff0000u) * (acc[i][3] + hb * __uint_as_float(yv.y & 0xffff0000u));
;           if (o == 0) {
;             uint2 ov; ov.x = pack2(r0, r1); ov.y = pack2(r2, r3);
;             *(uint2*)(YB + bb * HY_YS + t0) = ov;
;           } else {
;             u16* YS = (u16*)(p.ws + O_YS) + (rowoff + t0) * 1536 + 1024 + c;
;             YS[0] = f2bf(r0); YS[1536] = f2bf(r1); YS[2 * 1536] = f2bf(r2); YS[3 * 1536] = f2bf(r3);
;           }
.LBB0_393:
	ds_read_b64 v[32:33], v26 offset:32
	ds_read_b64 v[34:35], v27 offset:32
	s_andn2_b64 vcc, exec, s[40:41]
	s_mov_b64 s[4:5], -1
	s_waitcnt lgkmcnt(0)
	v_lshlrev_b32_e32 v36, 16, v32
	v_lshlrev_b32_e32 v37, 16, v34
	v_and_b32_e32 v34, 0xffff0000, v34
	v_and_b32_e32 v32, 0xffff0000, v32
	v_fma_f32 v29, s100, v34, v29
	v_lshlrev_b32_e32 v34, 16, v35
	v_mul_f32_e32 v29, v29, v32
	v_lshlrev_b32_e32 v32, 16, v33
	v_fma_f32 v30, s100, v34, v30
	v_mul_f32_e32 v30, v30, v32
	v_and_b32_e32 v32, 0xffff0000, v33
	v_and_b32_e32 v33, 0xffff0000, v35
	v_fmac_f32_e32 v31, s100, v33
	v_fma_f32 v28, s100, v37, v28
	v_mul_f32_e32 v31, v31, v32
	v_cndmask_b32_e64 v32, 0, 1, s[40:41]
	v_mul_f32_e32 v28, v28, v36
	v_cmp_ne_u32_e64 s[22:23], 1, v32
	s_cbranch_vccnz .LBB0_395
	v_or_b32_e32 v32, 16, v24
	v_ashrrev_i32_e32 v33, 31, v32
	v_lshl_add_u64 v[32:33], v[32:33], 0, v[68:69]
	v_lshl_add_u64 v[32:33], v[32:33], 1, v[80:81]
	v_cvt_pk_bf16_f32 v36, v28, v29
	v_cvt_pk_bf16_f32 v37, v30, v31
	global_store_dwordx2 v[32:33], v[36:37], off
	s_mov_b64 s[4:5], 0

; __device__ __forceinline__ u16 f2bf(float f) { unsigned r; asm("v_cvt_pk_bf16_f32 %0, %1, %1" : "=v"(r) : "v"(f)); return (u16)r; }
; __device__ __forceinline__ unsigned pack2(float a, float b) { unsigned r; asm("v_cvt_pk_bf16_f32 %0, %1, %2" : "=v"(r) : "v"(a), "v"(b)); return r; }
; __device__ __forceinline__ void hyena_task(const Params& p, int layer, int c, bool isctx, unsigned char* smem) {
;     ...
;       if (tt < 8) {
;         size_t rowoff = (size_t)rowbase + (size_t)bb * Ls;
; #pragma unroll
;         for (int i = 0; i < 8; i++) {
;           int t0 = 16 * (mi0 + i) + 4 * kg;
;           uint2 gq = *(const uint2*)(GT + bb * HY_YS + t0);
;           uint2 yv = *(const uint2*)(YT + bb * HY_YS + t0);
;           float r0 = __uint_as_float(gq.x << 16) * (acc[i][0] + hb * __uint_as_float(yv.x << 16));
;           float r1 = __uint_as_float(gq.x & 0xffff0000u) * (acc[i][1] + hb * __uint_as_float(yv.x & 0xffff0000u));
;           float r2 = __uint_as_float(gq.y << 16) * (acc[i][2] + hb * __uint_as_float(yv.y << 16));
;           float r3 = __uint_as_float(gq.y & 0xffff0000u) * (acc[i][3] + hb * __uint_as_float(yv.y & 0xffff0000u));
;           if (o == 0) {
;             uint2 ov; ov.x = pack2(r0, r1); ov.y = pack2(r2, r3);
;             *(uint2*)(YB + bb * HY_YS + t0) = ov;
;           } else {
;             u16* YS = (u16*)(p.ws + O_YS) + (rowoff + t0) * 1536 + 1024 + c;
;             YS[0] = f2bf(r0); YS[1536] = f2bf(r1); YS[2 * 1536] = f2bf(r2); YS[3 * 1536] = f2bf(r3);
;           }
.LBB0_397:
	ds_read_b64 v[28:29], v26 offset:64
	ds_read_b64 v[30:31], v27 offset:64
	s_and_b64 vcc, exec, s[22:23]
	s_mov_b64 s[4:5], -1
	s_waitcnt lgkmcnt(0)
	v_lshlrev_b32_e32 v32, 16, v28
	v_lshlrev_b32_e32 v33, 16, v30
	v_and_b32_e32 v30, 0xffff0000, v30
	v_and_b32_e32 v28, 0xffff0000, v28
	v_fma_f32 v21, s100, v30, v21
	v_lshlrev_b32_e32 v30, 16, v31
	v_mul_f32_e32 v21, v21, v28
	v_lshlrev_b32_e32 v28, 16, v29
	v_fma_f32 v22, s100, v30, v22
	v_mul_f32_e32 v22, v22, v28
	v_and_b32_e32 v28, 0xffff0000, v29
	v_and_b32_e32 v29, 0xffff0000, v31
	v_fma_f32 v20, s100, v33, v20
	v_fmac_f32_e32 v23, s100, v29
	v_mul_f32_e32 v20, v20, v32
	v_mul_f32_e32 v23, v23, v28
	s_cbranch_vccnz .LBB0_399
	v_or_b32_e32 v28, 32, v24
	v_ashrrev_i32_e32 v29, 31, v28
	v_lshl_add_u64 v[28:29], v[28:29], 0, v[68:69]
	v_lshl_add_u64 v[28:29], v[28:29], 1, v[80:81]
	v_cvt_pk_bf16_f32 v32, v20, v21
	v_cvt_pk_bf16_f32 v33, v22, v23
	global_store_dwordx2 v[28:29], v[32:33], off
	s_mov_b64 s[4:5], 0

; __device__ __forceinline__ u16 f2bf(float f) { unsigned r; asm("v_cvt_pk_bf16_f32 %0, %1, %1" : "=v"(r) : "v"(f)); return (u16)r; }
; __device__ __forceinline__ unsigned pack2(float a, float b) { unsigned r; asm("v_cvt_pk_bf16_f32 %0, %1, %2" : "=v"(r) : "v"(a), "v"(b)); return r; }
; __device__ __forceinline__ void hyena_task(const Params& p, int layer, int c, bool isctx, unsigned char* smem) {
;     ...
;       if (tt < 8) {
;         size_t rowoff = (size_t)rowbase + (size_t)bb * Ls;
; #pragma unroll
;         for (int i = 0; i < 8; i++) {
;           int t0 = 16 * (mi0 + i) + 4 * kg;
;           uint2 gq = *(const uint2*)(GT + bb * HY_YS + t0);
;           uint2 yv = *(const uint2*)(YT + bb * HY_YS + t0);
;           float r0 = __uint_as_float(gq.x << 16) * (acc[i][0] + hb * __uint_as_float(yv.x << 16));
;           float r1 = __uint_as_float(gq.x & 0xffff0000u) * (acc[i][1] + hb * __uint_as_float(yv.x & 0xffff0000u));
;           float r2 = __uint_as_float(gq.y << 16) * (acc[i][2] + hb * __uint_as_float(yv.y << 16));
;           float r3 = __uint_as_float(gq.y & 0xffff0000u) * (acc[i][3] + hb * __uint_as_float(yv.y & 0xffff0000u));
;           if (o == 0) {
;             uint2 ov; ov.x = pack2(r0, r1); ov.y = pack2(r2, r3);
;             *(uint2*)(YB + bb * HY_YS + t0) = ov;
;           } else {
;             u16* YS = (u16*)(p.ws + O_YS) + (rowoff + t0) * 1536 + 1024 + c;
;             YS[0] = f2bf(r0); YS[1536] = f2bf(r1); YS[2 * 1536] = f2bf(r2); YS[3 * 1536] = f2bf(r3);
;           }
.LBB0_401:
	ds_read_b64 v[20:21], v26 offset:96
	ds_read_b64 v[22:23], v27 offset:96
	s_and_b64 vcc, exec, s[22:23]
	s_mov_b64 s[4:5], -1
	s_waitcnt lgkmcnt(0)
	v_lshlrev_b32_e32 v28, 16, v20
	v_lshlrev_b32_e32 v29, 16, v22
	v_and_b32_e32 v22, 0xffff0000, v22
	v_and_b32_e32 v20, 0xffff0000, v20
	v_fma_f32 v17, s100, v22, v17
	v_lshlrev_b32_e32 v22, 16, v23
	v_mul_f32_e32 v17, v17, v20
	v_lshlrev_b32_e32 v20, 16, v21
	v_fma_f32 v18, s100, v22, v18
	v_mul_f32_e32 v18, v18, v20
	v_and_b32_e32 v20, 0xffff0000, v21
	v_and_b32_e32 v21, 0xffff0000, v23
	v_fma_f32 v16, s100, v29, v16
	v_fmac_f32_e32 v19, s100, v21
	v_mul_f32_e32 v16, v16, v28
	v_mul_f32_e32 v19, v19, v20
	s_cbranch_vccnz .LBB0_403
	v_or_b32_e32 v20, 48, v24
	v_ashrrev_i32_e32 v21, 31, v20
	v_lshl_add_u64 v[20:21], v[20:21], 0, v[68:69]
	v_lshl_add_u64 v[20:21], v[20:21], 1, v[80:81]
	v_cvt_pk_bf16_f32 v28, v16, v17
	v_cvt_pk_bf16_f32 v29, v18, v19
	global_store_dwordx2 v[20:21], v[28:29], off
	s_mov_b64 s[4:5], 0

; __device__ __forceinline__ u16 f2bf(float f) { unsigned r; asm("v_cvt_pk_bf16_f32 %0, %1, %1" : "=v"(r) : "v"(f)); return (u16)r; }
; __device__ __forceinline__ unsigned pack2(float a, float b) { unsigned r; asm("v_cvt_pk_bf16_f32 %0, %1, %2" : "=v"(r) : "v"(a), "v"(b)); return r; }
; __device__ __forceinline__ void hyena_task(const Params& p, int layer, int c, bool isctx, unsigned char* smem) {
;     ...
;       if (tt < 8) {
;         size_t rowoff = (size_t)rowbase + (size_t)bb * Ls;
; #pragma unroll
;         for (int i = 0; i < 8; i++) {
;           int t0 = 16 * (mi0 + i) + 4 * kg;
;           uint2 gq = *(const uint2*)(GT + bb * HY_YS + t0);
;           uint2 yv = *(const uint2*)(YT + bb * HY_YS + t0);
;           float r0 = __uint_as_float(gq.x << 16) * (acc[i][0] + hb * __uint_as_float(yv.x << 16));
;           float r1 = __uint_as_float(gq.x & 0xffff0000u) * (acc[i][1] + hb * __uint_as_float(yv.x & 0xffff0000u));
;           float r2 = __uint_as_float(gq.y << 16) * (acc[i][2] + hb * __uint_as_float(yv.y << 16));
;           float r3 = __uint_as_float(gq.y & 0xffff0000u) * (acc[i][3] + hb * __uint_as_float(yv.y & 0xffff0000u));
;           if (o == 0) {
;             uint2 ov; ov.x = pack2(r0, r1); ov.y = pack2(r2, r3);
;             *(uint2*)(YB + bb * HY_YS + t0) = ov;
;           } else {
;             u16* YS = (u16*)(p.ws + O_YS) + (rowoff + t0) * 1536 + 1024 + c;
;             YS[0] = f2bf(r0); YS[1536] = f2bf(r1); YS[2 * 1536] = f2bf(r2); YS[3 * 1536] = f2bf(r3);
;           }
.LBB0_405:
	ds_read_b64 v[16:17], v26 offset:128
	ds_read_b64 v[18:19], v27 offset:128
	s_and_b64 vcc, exec, s[22:23]
	s_mov_b64 s[4:5], -1
	s_waitcnt lgkmcnt(0)
	v_lshlrev_b32_e32 v20, 16, v16
	v_lshlrev_b32_e32 v21, 16, v18
	v_and_b32_e32 v18, 0xffff0000, v18
	v_and_b32_e32 v16, 0xffff0000, v16
	v_fma_f32 v13, s100, v18, v13
	v_lshlrev_b32_e32 v18, 16, v19
	v_mul_f32_e32 v13, v13, v16
	v_lshlrev_b32_e32 v16, 16, v17
	v_fma_f32 v14, s100, v18, v14
	v_mul_f32_e32 v14, v14, v16
	v_and_b32_e32 v16, 0xffff0000, v17
	v_and_b32_e32 v17, 0xffff0000, v19
	v_fma_f32 v12, s100, v21, v12
	v_fmac_f32_e32 v15, s100, v17
	v_mul_f32_e32 v12, v12, v20
	v_mul_f32_e32 v15, v15, v16
	s_cbranch_vccnz .LBB0_407
	v_or_b32_e32 v16, 64, v24
	v_ashrrev_i32_e32 v17, 31, v16
	v_lshl_add_u64 v[16:17], v[16:17], 0, v[68:69]
	v_lshl_add_u64 v[16:17], v[16:17], 1, v[80:81]
	v_cvt_pk_bf16_f32 v20, v12, v13
	v_cvt_pk_bf16_f32 v21, v14, v15
	global_store_dwordx2 v[16:17], v[20:21], off
	s_mov_b64 s[4:5], 0

; __device__ __forceinline__ u16 f2bf(float f) { unsigned r; asm("v_cvt_pk_bf16_f32 %0, %1, %1" : "=v"(r) : "v"(f)); return (u16)r; }
; __device__ __forceinline__ unsigned pack2(float a, float b) { unsigned r; asm("v_cvt_pk_bf16_f32 %0, %1, %2" : "=v"(r) : "v"(a), "v"(b)); return r; }
; __device__ __forceinline__ void hyena_task(const Params& p, int layer, int c, bool isctx, unsigned char* smem) {
;     ...
;       if (tt < 8) {
;         size_t rowoff = (size_t)rowbase + (size_t)bb * Ls;
; #pragma unroll
;         for (int i = 0; i < 8; i++) {
;           int t0 = 16 * (mi0 + i) + 4 * kg;
;           uint2 gq = *(const uint2*)(GT + bb * HY_YS + t0);
;           uint2 yv = *(const uint2*)(YT + bb * HY_YS + t0);
;           float r0 = __uint_as_float(gq.x << 16) * (acc[i][0] + hb * __uint_as_float(yv.x << 16));
;           float r1 = __uint_as_float(gq.x & 0xffff0000u) * (acc[i][1] + hb * __uint_as_float(yv.x & 0xffff0000u));
;           float r2 = __uint_as_float(gq.y << 16) * (acc[i][2] + hb * __uint_as_float(yv.y << 16));
;           float r3 = __uint_as_float(gq.y & 0xffff0000u) * (acc[i][3] + hb * __uint_as_float(yv.y & 0xffff0000u));
;           if (o == 0) {
;             uint2 ov; ov.x = pack2(r0, r1); ov.y = pack2(r2, r3);
;             *(uint2*)(YB + bb * HY_YS + t0) = ov;
;           } else {
;             u16* YS = (u16*)(p.ws + O_YS) + (rowoff + t0) * 1536 + 1024 + c;
;             YS[0] = f2bf(r0); YS[1536] = f2bf(r1); YS[2 * 1536] = f2bf(r2); YS[3 * 1536] = f2bf(r3);
;           }
.LBB0_409:
	ds_read_b64 v[12:13], v26 offset:160
	ds_read_b64 v[14:15], v27 offset:160
	s_and_b64 vcc, exec, s[22:23]
	s_mov_b64 s[4:5], -1
	s_waitcnt lgkmcnt(0)
	v_lshlrev_b32_e32 v16, 16, v12
	v_lshlrev_b32_e32 v17, 16, v14
	v_and_b32_e32 v14, 0xffff0000, v14
	v_and_b32_e32 v12, 0xffff0000, v12
	v_fma_f32 v9, s100, v14, v9
	v_lshlrev_b32_e32 v14, 16, v15
	v_mul_f32_e32 v9, v9, v12
	v_lshlrev_b32_e32 v12, 16, v13
	v_fma_f32 v10, s100, v14, v10
	v_mul_f32_e32 v10, v10, v12
	v_and_b32_e32 v12, 0xffff0000, v13
	v_and_b32_e32 v13, 0xffff0000, v15
	v_fma_f32 v8, s100, v17, v8
	v_fmac_f32_e32 v11, s100, v13
	v_mul_f32_e32 v8, v8, v16
	v_mul_f32_e32 v11, v11, v12
	s_cbranch_vccnz .LBB0_411
	v_or_b32_e32 v12, 0x50, v24
	v_ashrrev_i32_e32 v13, 31, v12
	v_lshl_add_u64 v[12:13], v[12:13], 0, v[68:69]
	v_lshl_add_u64 v[12:13], v[12:13], 1, v[80:81]
	v_cvt_pk_bf16_f32 v16, v8, v9
	v_cvt_pk_bf16_f32 v17, v10, v11
	global_store_dwordx2 v[12:13], v[16:17], off
	s_mov_b64 s[4:5], 0

; __device__ __forceinline__ u16 f2bf(float f) { unsigned r; asm("v_cvt_pk_bf16_f32 %0, %1, %1" : "=v"(r) : "v"(f)); return (u16)r; }
; __device__ __forceinline__ unsigned pack2(float a, float b) { unsigned r; asm("v_cvt_pk_bf16_f32 %0, %1, %2" : "=v"(r) : "v"(a), "v"(b)); return r; }
; __device__ __forceinline__ void hyena_task(const Params& p, int layer, int c, bool isctx, unsigned char* smem) {
;     ...
;       if (tt < 8) {
;         size_t rowoff = (size_t)rowbase + (size_t)bb * Ls;
; #pragma unroll
;         for (int i = 0; i < 8; i++) {
;           int t0 = 16 * (mi0 + i) + 4 * kg;
;           uint2 gq = *(const uint2*)(GT + bb * HY_YS + t0);
;           uint2 yv = *(const uint2*)(YT + bb * HY_YS + t0);
;           float r0 = __uint_as_float(gq.x << 16) * (acc[i][0] + hb * __uint_as_float(yv.x << 16));
;           float r1 = __uint_as_float(gq.x & 0xffff0000u) * (acc[i][1] + hb * __uint_as_float(yv.x & 0xffff0000u));
;           float r2 = __uint_as_float(gq.y << 16) * (acc[i][2] + hb * __uint_as_float(yv.y << 16));
;           float r3 = __uint_as_float(gq.y & 0xffff0000u) * (acc[i][3] + hb * __uint_as_float(yv.y & 0xffff0000u));
;           if (o == 0) {
;             uint2 ov; ov.x = pack2(r0, r1); ov.y = pack2(r2, r3);
;             *(uint2*)(YB + bb * HY_YS + t0) = ov;
;           } else {
;             u16* YS = (u16*)(p.ws + O_YS) + (rowoff + t0) * 1536 + 1024 + c;
;             YS[0] = f2bf(r0); YS[1536] = f2bf(r1); YS[2 * 1536] = f2bf(r2); YS[3 * 1536] = f2bf(r3);
;           }
.LBB0_413:
	ds_read_b64 v[8:9], v26 offset:192
	ds_read_b64 v[10:11], v27 offset:192
	s_and_b64 vcc, exec, s[22:23]
	s_mov_b64 s[4:5], -1
	s_waitcnt lgkmcnt(0)
	v_lshlrev_b32_e32 v12, 16, v8
	v_lshlrev_b32_e32 v13, 16, v10
	v_and_b32_e32 v10, 0xffff0000, v10
	v_and_b32_e32 v8, 0xffff0000, v8
	v_fma_f32 v5, s100, v10, v5
	v_lshlrev_b32_e32 v10, 16, v11
	v_mul_f32_e32 v5, v5, v8
	v_lshlrev_b32_e32 v8, 16, v9
	v_fma_f32 v6, s100, v10, v6
	v_mul_f32_e32 v6, v6, v8
	v_and_b32_e32 v8, 0xffff0000, v9
	v_and_b32_e32 v9, 0xffff0000, v11
	v_fma_f32 v4, s100, v13, v4
	v_fmac_f32_e32 v7, s100, v9
	v_mul_f32_e32 v4, v4, v12
	v_mul_f32_e32 v7, v7, v8
	s_cbranch_vccnz .LBB0_415
	v_or_b32_e32 v8, 0x60, v24
	v_ashrrev_i32_e32 v9, 31, v8
	v_lshl_add_u64 v[8:9], v[8:9], 0, v[68:69]
	v_lshl_add_u64 v[8:9], v[8:9], 1, v[80:81]
	v_cvt_pk_bf16_f32 v12, v4, v5
	v_cvt_pk_bf16_f32 v13, v6, v7
	global_store_dwordx2 v[8:9], v[12:13], off
	s_mov_b64 s[4:5], 0

; __device__ __forceinline__ u16 f2bf(float f) { unsigned r; asm("v_cvt_pk_bf16_f32 %0, %1, %1" : "=v"(r) : "v"(f)); return (u16)r; }
; __device__ __forceinline__ unsigned pack2(float a, float b) { unsigned r; asm("v_cvt_pk_bf16_f32 %0, %1, %2" : "=v"(r) : "v"(a), "v"(b)); return r; }
; __device__ __forceinline__ void hyena_task(const Params& p, int layer, int c, bool isctx, unsigned char* smem) {
;     ...
;       if (tt < 8) {
;         size_t rowoff = (size_t)rowbase + (size_t)bb * Ls;
; #pragma unroll
;         for (int i = 0; i < 8; i++) {
;           int t0 = 16 * (mi0 + i) + 4 * kg;
;           uint2 gq = *(const uint2*)(GT + bb * HY_YS + t0);
;           uint2 yv = *(const uint2*)(YT + bb * HY_YS + t0);
;           float r0 = __uint_as_float(gq.x << 16) * (acc[i][0] + hb * __uint_as_float(yv.x << 16));
;           float r1 = __uint_as_float(gq.x & 0xffff0000u) * (acc[i][1] + hb * __uint_as_float(yv.x & 0xffff0000u));
;           float r2 = __uint_as_float(gq.y << 16) * (acc[i][2] + hb * __uint_as_float(yv.y << 16));
;           float r3 = __uint_as_float(gq.y & 0xffff0000u) * (acc[i][3] + hb * __uint_as_float(yv.y & 0xffff0000u));
;           if (o == 0) {
;             uint2 ov; ov.x = pack2(r0, r1); ov.y = pack2(r2, r3);
;             *(uint2*)(YB + bb * HY_YS + t0) = ov;
;           } else {
;             u16* YS = (u16*)(p.ws + O_YS) + (rowoff + t0) * 1536 + 1024 + c;
;             YS[0] = f2bf(r0); YS[1536] = f2bf(r1); YS[2 * 1536] = f2bf(r2); YS[3 * 1536] = f2bf(r3);
;           }
.LBB0_417:
	ds_read_b64 v[4:5], v26 offset:224
	ds_read_b64 v[6:7], v27 offset:224
	s_and_b64 vcc, exec, s[22:23]
	s_mov_b64 s[4:5], -1
	s_waitcnt lgkmcnt(0)
	v_lshlrev_b32_e32 v8, 16, v4
	v_lshlrev_b32_e32 v9, 16, v6
	v_and_b32_e32 v6, 0xffff0000, v6
	v_and_b32_e32 v4, 0xffff0000, v4
	v_fma_f32 v1, s100, v6, v1
	v_lshlrev_b32_e32 v6, 16, v7
	v_mul_f32_e32 v1, v1, v4
	v_lshlrev_b32_e32 v4, 16, v5
	v_fma_f32 v2, s100, v6, v2
	v_mul_f32_e32 v2, v2, v4
	v_and_b32_e32 v4, 0xffff0000, v5
	v_and_b32_e32 v5, 0xffff0000, v7
	v_fma_f32 v0, s100, v9, v0
	v_fmac_f32_e32 v3, s100, v5
	v_mul_f32_e32 v0, v0, v8
	v_mul_f32_e32 v3, v3, v4
	s_cbranch_vccnz .LBB0_419
	v_or_b32_e32 v4, 0x70, v24
	v_ashrrev_i32_e32 v5, 31, v4
	v_lshl_add_u64 v[4:5], v[4:5], 0, v[68:69]
	v_lshl_add_u64 v[4:5], v[4:5], 1, v[80:81]
	v_cvt_pk_bf16_f32 v8, v0, v1
	v_cvt_pk_bf16_f32 v9, v2, v3
	global_store_dwordx2 v[4:5], v[8:9], off
	s_mov_b64 s[4:5], 0

; __device__ __forceinline__ unsigned pack2(float a, float b) { unsigned r; asm("v_cvt_pk_bf16_f32 %0, %1, %2" : "=v"(r) : "v"(a), "v"(b)); return r; }
; __device__ __forceinline__ void attn_item(const Params& p, int layer, bool isctx, int item, unsigned char* smem) {
;     ...
; #pragma unroll
;     for (int k4 = 0; k4 < 4; k4++) {
;       f32x16 st;
; #pragma unroll
;       for (int r = 0; r < 16; r++) st[r] = 0.f;
; #pragma unroll
;       for (int ks = 0; ks < 4; ks++) {
;         bf16x8 kf = *(const bf16x8*)(Ks + (k4 * 32 + (lane & 31)) * 72 + ks * 16 + hh * 8);
;         st = __builtin_amdgcn_mfma_f32_32x32x16_bf16(kf, qf[ks], st, 0, 0, 0);
;       }
;       float pe[16];
; #pragma unroll
;       for (int r = 0; r < 16; r++) {
;         int kl = k4 * 32 + (r & 3) + 8 * (r >> 2) + 4 * hh;
;         float e = __expf(st[r] * 0.125f);
;         bool valid = (mtype * kl) <= mq;
;         e = valid ? e : 0.f;
;         pe[r] = e; rsum += e;
;       }
;       bf16x8 pb[2];
; #pragma unroll
;       for (int s = 0; s < 2; s++) {
;         union { bf16x8 v; unsigned w[4]; } cv;
; #pragma unroll
;         for (int q = 0; q < 4; q++) cv.w[q] = pack2(pe[8 * s + 2 * q], pe[8 * s + 2 * q + 1]);
;         pb[s] = cv.v;
;       }
; #pragma unroll
;       for (int mt = 0; mt < 2; mt++)
; #pragma unroll
;         for (int s = 0; s < 2; s++) {
;           const u16* vp = Vt + (mt * 32 + (lane & 31)) * 136 + k4 * 32 + 16 * s + 4 * hh;
;           union { bf16x8 v; uint2 h2[2]; } av;
;           av.h2[0] = *(const uint2*)vp;
;           av.h2[1] = *(const uint2*)(vp + 8);
;           oacc[mt] = __builtin_amdgcn_mfma_f32_32x32x16_bf16(av.v, pb[s], oacc[mt], 0, 0, 0);
;         }
.LBB0_477:
	v_ashrrev_i32_e32 v81, 31, v80
	v_lshlrev_b64 v[32:33], 8, v[80:81]
	v_lshl_add_u64 v[32:33], v[70:71], 0, v[32:33]
	s_waitcnt lgkmcnt(0)
	s_barrier
	global_load_dwordx4 v[32:35], v[32:33], off
	v_ashrrev_i32_e32 v83, 31, v82
	v_add_u32_e32 v80, 0x80, v80
	s_waitcnt vmcnt(0) lgkmcnt(0)
	ds_write_b128 v72, v[32:35]
	v_lshl_add_u64 v[32:33], v[78:79], 0, s[8:9]
	global_load_dwordx4 v[32:35], v[32:33], off
	s_waitcnt vmcnt(0) lgkmcnt(0)
	ds_write_b128 v69, v[32:35]
	v_lshlrev_b64 v[32:33], 8, v[82:83]
	v_lshl_add_u64 v[32:33], v[70:71], 0, v[32:33]
	global_load_dwordx4 v[32:35], v[32:33], off
	v_add_u32_e32 v82, 0x80, v82
	s_waitcnt vmcnt(0) lgkmcnt(0)
	ds_write_b128 v74, v[32:35]
	v_lshl_add_u64 v[32:33], v[76:77], 0, s[8:9]
	global_load_dwordx4 v[32:35], v[32:33], off
	s_add_u32 s8, s8, 0x100
	s_addc_u32 s9, s9, 0
	s_cmpk_lg_i32 s8, 0x200
	s_waitcnt vmcnt(0) lgkmcnt(0)
	ds_write_b128 v73, v[32:35]
	s_waitcnt lgkmcnt(0)
	s_barrier
	ds_read_b128 v[32:35], v75
	ds_read_b128 v[86:89], v75 offset:32
	s_waitcnt lgkmcnt(1)
	v_mfma_f32_32x32x16_bf16 v[32:47], v[32:35], v[56:59], 0
	s_waitcnt lgkmcnt(0)
	v_mfma_f32_32x32x16_bf16 v[32:47], v[86:89], v[48:51], v[32:47]
	ds_read_b128 v[86:89], v75 offset:64
	s_waitcnt lgkmcnt(0)
	v_mfma_f32_32x32x16_bf16 v[32:47], v[86:89], v[52:55], v[32:47]
	ds_read_b128 v[86:89], v75 offset:96
	s_waitcnt lgkmcnt(0)
	v_mfma_f32_32x32x16_bf16 v[32:47], v[86:89], v[60:63], v[32:47]
	s_nop 11
	v_mul_f32_e32 v32, 0x3e38aa3b, v32
	v_exp_f32_e32 v81, v32
	v_mul_f32_e32 v32, 0x3e38aa3b, v33
	v_exp_f32_e32 v83, v32
	v_mul_f32_e32 v32, 0x3e38aa3b, v34
	v_exp_f32_e32 v86, v32
	v_mul_f32_e32 v32, 0x3e38aa3b, v35
	v_exp_f32_e32 v87, v32
	v_mul_f32_e32 v32, 0x3e38aa3b, v36
	v_exp_f32_e32 v88, v32
	v_mul_f32_e32 v32, 0x3e38aa3b, v37
	v_exp_f32_e32 v89, v32
	v_mul_f32_e32 v32, 0x3e38aa3b, v38
	v_exp_f32_e32 v90, v32
	v_mul_f32_e32 v32, 0x3e38aa3b, v39
	v_exp_f32_e32 v91, v32
	v_mul_f32_e32 v32, 0x3e38aa3b, v40
	v_exp_f32_e32 v40, v32
	v_mul_f32_e32 v32, 0x3e38aa3b, v41
	v_exp_f32_e32 v41, v32
	v_mul_f32_e32 v32, 0x3e38aa3b, v42
	v_exp_f32_e32 v42, v32
	v_mul_f32_e32 v32, 0x3e38aa3b, v43
	v_exp_f32_e32 v43, v32
	v_mul_f32_e32 v32, 0x3e38aa3b, v44
	v_exp_f32_e32 v44, v32
	v_mul_f32_e32 v32, 0x3e38aa3b, v45
	v_exp_f32_e32 v45, v32
	v_mul_f32_e32 v32, 0x3e38aa3b, v46
	v_exp_f32_e32 v46, v32
	v_mul_f32_e32 v32, 0x3e000000, v47
	v_add_f32_e32 v47, v85, v81
	v_add_f32_e32 v47, v83, v47
	v_add_f32_e32 v47, v86, v47
	v_add_f32_e32 v47, v87, v47
	v_add_f32_e32 v47, v88, v47
	v_add_f32_e32 v47, v89, v47
	v_add_f32_e32 v47, v90, v47
	v_add_f32_e32 v47, v91, v47
	v_cvt_pk_bf16_f32 v36, v40, v41
	v_add_f32_e32 v40, v40, v47
	v_add_f32_e32 v40, v41, v40
	v_add_f32_e32 v40, v42, v40
	v_add_f32_e32 v40, v43, v40
	v_mul_f32_e32 v32, 0x3fb8aa3b, v32
	v_add_f32_e32 v40, v44, v40
	v_exp_f32_e32 v92, v32
	v_cvt_pk_bf16_f32 v32, v81, v83
	v_add_f32_e32 v40, v45, v40
	v_add_u32_e32 v81, 0x4800, v84
	v_cvt_pk_bf16_f32 v37, v42, v43
	v_cvt_pk_bf16_f32 v38, v44, v45
	v_cvt_pk_bf16_f32 v39, v46, v92
	v_add_f32_e32 v85, v46, v40
	ds_read2_b64 v[40:43], v81 offset1:2
	ds_read2_b64 v[44:47], v81 offset0:4 offset1:6
	v_add_u32_e32 v83, 0x6800, v84
	v_cvt_pk_bf16_f32 v33, v86, v87
	v_cvt_pk_bf16_f32 v34, v88, v89
	v_cvt_pk_bf16_f32 v35, v90, v91
	ds_read_b128 v[86:89], v75 offset:4640
	s_waitcnt lgkmcnt(2)
	v_mfma_f32_32x32x16_bf16 v[0:15], v[40:43], v[32:35], v[0:15]
	ds_read2_b64 v[40:43], v83 offset0:64 offset1:66
	v_add_f32_e32 v85, v92, v85
	s_waitcnt lgkmcnt(0)
	v_mfma_f32_32x32x16_bf16 v[16:31], v[40:43], v[32:35], v[16:31]
	ds_read2_b64 v[32:35], v83 offset0:68 offset1:70
	s_waitcnt lgkmcnt(0)
	v_mfma_f32_32x32x16_bf16 v[16:31], v[32:35], v[36:39], v[16:31]
	ds_read_b128 v[32:35], v75 offset:4608
	v_mfma_f32_32x32x16_bf16 v[0:15], v[44:47], v[36:39], v[0:15]
	s_waitcnt lgkmcnt(0)
	v_mfma_f32_32x32x16_bf16 v[32:47], v[32:35], v[56:59], 0
	v_mfma_f32_32x32x16_bf16 v[32:47], v[86:89], v[48:51], v[32:47]
	ds_read_b128 v[86:89], v75 offset:4672
	s_waitcnt lgkmcnt(0)
	v_mfma_f32_32x32x16_bf16 v[32:47], v[86:89], v[52:55], v[32:47]
	ds_read_b128 v[86:89], v75 offset:4704
	s_waitcnt lgkmcnt(0)
	v_mfma_f32_32x32x16_bf16 v[32:47], v[86:89], v[60:63], v[32:47]
	s_nop 11
	v_mul_f32_e32 v32, 0x3e38aa3b, v32
	v_exp_f32_e32 v86, v32
	v_mul_f32_e32 v32, 0x3e38aa3b, v33
	v_exp_f32_e32 v87, v32
	v_mul_f32_e32 v32, 0x3e38aa3b, v34
	v_exp_f32_e32 v88, v32
	v_mul_f32_e32 v32, 0x3e38aa3b, v35
	v_exp_f32_e32 v89, v32
	v_mul_f32_e32 v32, 0x3e38aa3b, v36
	v_exp_f32_e32 v90, v32
	v_mul_f32_e32 v32, 0x3e38aa3b, v37
	v_exp_f32_e32 v91, v32
	v_mul_f32_e32 v32, 0x3e38aa3b, v38
	v_exp_f32_e32 v92, v32
	v_mul_f32_e32 v32, 0x3e38aa3b, v39
	v_exp_f32_e32 v93, v32
	v_mul_f32_e32 v32, 0x3e38aa3b, v40
	v_exp_f32_e32 v40, v32
	v_mul_f32_e32 v32, 0x3e38aa3b, v41
	v_exp_f32_e32 v41, v32
	v_mul_f32_e32 v32, 0x3e38aa3b, v42
	v_add_f32_e32 v85, v85, v86
	v_add_f32_e32 v85, v87, v85
	v_exp_f32_e32 v42, v32
	v_mul_f32_e32 v32, 0x3e38aa3b, v43
	v_add_f32_e32 v85, v88, v85
	v_add_f32_e32 v85, v89, v85
	v_exp_f32_e32 v43, v32
	v_mul_f32_e32 v32, 0x3e38aa3b, v44
	v_add_f32_e32 v85, v90, v85
	v_add_f32_e32 v85, v91, v85
	v_exp_f32_e32 v44, v32
	v_mul_f32_e32 v32, 0x3e38aa3b, v45
	v_add_f32_e32 v85, v92, v85
	v_add_f32_e32 v85, v93, v85
	v_exp_f32_e32 v45, v32
	v_mul_f32_e32 v32, 0x3e38aa3b, v46
	v_cvt_pk_bf16_f32 v36, v40, v41
	v_add_f32_e32 v40, v40, v85
	v_add_f32_e32 v40, v41, v40
	v_exp_f32_e32 v46, v32
	v_add_f32_e32 v40, v42, v40
	v_add_f32_e32 v40, v43, v40
	v_add_f32_e32 v40, v44, v40
	v_add_f32_e32 v40, v45, v40
	v_cvt_pk_bf16_f32 v37, v42, v43
	v_cvt_pk_bf16_f32 v38, v44, v45
	v_add_f32_e32 v44, v46, v40
	ds_read2_b64 v[40:43], v81 offset0:8 offset1:10
	v_mul_f32_e32 v32, 0x3e38aa3b, v47
	v_exp_f32_e32 v47, v32
	v_cvt_pk_bf16_f32 v32, v86, v87
	v_cvt_pk_bf16_f32 v33, v88, v89
	v_cvt_pk_bf16_f32 v34, v90, v91
	v_cvt_pk_bf16_f32 v35, v92, v93
	v_cvt_pk_bf16_f32 v39, v46, v47
	ds_read_b128 v[86:89], v75 offset:9248
	s_waitcnt lgkmcnt(1)
; __device__ __forceinline__ unsigned pack2(float a, float b) { unsigned r; asm("v_cvt_pk_bf16_f32 %0, %1, %2" : "=v"(r) : "v"(a), "v"(b)); return r; }
; __device__ __forceinline__ void attn_item(const Params& p, int layer, bool isctx, int item, unsigned char* smem) {
;     ...
; #pragma unroll
;     for (int k4 = 0; k4 < 4; k4++) {
;       f32x16 st;
; #pragma unroll
;       for (int r = 0; r < 16; r++) st[r] = 0.f;
; #pragma unroll
;       for (int ks = 0; ks < 4; ks++) {
;         bf16x8 kf = *(const bf16x8*)(Ks + (k4 * 32 + (lane & 31)) * 72 + ks * 16 + hh * 8);
;         st = __builtin_amdgcn_mfma_f32_32x32x16_bf16(kf, qf[ks], st, 0, 0, 0);
;       }
;       float pe[16];
; #pragma unroll
;       for (int r = 0; r < 16; r++) {
;         int kl = k4 * 32 + (r & 3) + 8 * (r >> 2) + 4 * hh;
;         float e = __expf(st[r] * 0.125f);
;         bool valid = (mtype * kl) <= mq;
;         e = valid ? e : 0.f;
;         pe[r] = e; rsum += e;
;       }
;       bf16x8 pb[2];
; #pragma unroll
;       for (int s = 0; s < 2; s++) {
;         union { bf16x8 v; unsigned w[4]; } cv;
; #pragma unroll
;         for (int q = 0; q < 4; q++) cv.w[q] = pack2(pe[8 * s + 2 * q], pe[8 * s + 2 * q + 1]);
;         pb[s] = cv.v;
;       }
; #pragma unroll
;       for (int mt = 0; mt < 2; mt++)
; #pragma unroll
;         for (int s = 0; s < 2; s++) {
;           const u16* vp = Vt + (mt * 32 + (lane & 31)) * 136 + k4 * 32 + 16 * s + 4 * hh;
;           union { bf16x8 v; uint2 h2[2]; } av;
;           av.h2[0] = *(const uint2*)vp;
;           av.h2[1] = *(const uint2*)(vp + 8);
;           oacc[mt] = __builtin_amdgcn_mfma_f32_32x32x16_bf16(av.v, pb[s], oacc[mt], 0, 0, 0);
;         }
;     }
	v_mfma_f32_32x32x16_bf16 v[0:15], v[40:43], v[32:35], v[0:15]
	ds_read2_b64 v[40:43], v81 offset0:12 offset1:14
	v_add_f32_e32 v85, v47, v44
	s_waitcnt lgkmcnt(0)
	v_mfma_f32_32x32x16_bf16 v[0:15], v[40:43], v[36:39], v[0:15]
	ds_read2_b64 v[40:43], v83 offset0:72 offset1:74
	s_waitcnt lgkmcnt(0)
	v_mfma_f32_32x32x16_bf16 v[16:31], v[40:43], v[32:35], v[16:31]
	ds_read2_b64 v[32:35], v83 offset0:76 offset1:78
	s_waitcnt lgkmcnt(0)
	v_mfma_f32_32x32x16_bf16 v[16:31], v[32:35], v[36:39], v[16:31]
	ds_read_b128 v[32:35], v75 offset:9216
	s_waitcnt lgkmcnt(0)
	v_mfma_f32_32x32x16_bf16 v[32:47], v[32:35], v[56:59], 0
	v_mfma_f32_32x32x16_bf16 v[32:47], v[86:89], v[48:51], v[32:47]
	ds_read_b128 v[86:89], v75 offset:9280
	s_waitcnt lgkmcnt(0)
	v_mfma_f32_32x32x16_bf16 v[32:47], v[86:89], v[52:55], v[32:47]
	ds_read_b128 v[86:89], v75 offset:9312
	s_waitcnt lgkmcnt(0)
	v_mfma_f32_32x32x16_bf16 v[32:47], v[86:89], v[60:63], v[32:47]
	s_nop 11
	v_mul_f32_e32 v32, 0x3e38aa3b, v32
	v_exp_f32_e32 v86, v32
	v_mul_f32_e32 v32, 0x3e38aa3b, v33
	v_exp_f32_e32 v87, v32
	v_mul_f32_e32 v32, 0x3e38aa3b, v34
	v_exp_f32_e32 v88, v32
	v_mul_f32_e32 v32, 0x3e38aa3b, v35
	v_exp_f32_e32 v89, v32
	v_mul_f32_e32 v32, 0x3e38aa3b, v36
	v_exp_f32_e32 v90, v32
	v_mul_f32_e32 v32, 0x3e38aa3b, v37
	v_exp_f32_e32 v91, v32
	v_mul_f32_e32 v32, 0x3e38aa3b, v38
	v_exp_f32_e32 v92, v32
	v_mul_f32_e32 v32, 0x3e38aa3b, v39
	v_exp_f32_e32 v93, v32
	v_mul_f32_e32 v32, 0x3e38aa3b, v40
	v_exp_f32_e32 v40, v32
	v_mul_f32_e32 v32, 0x3e38aa3b, v41
	v_exp_f32_e32 v41, v32
	v_mul_f32_e32 v32, 0x3e38aa3b, v42
	v_add_f32_e32 v85, v85, v86
	v_add_f32_e32 v85, v87, v85
	v_exp_f32_e32 v42, v32
	v_mul_f32_e32 v32, 0x3e38aa3b, v43
	v_add_f32_e32 v85, v88, v85
	v_add_f32_e32 v85, v89, v85
	v_exp_f32_e32 v43, v32
	v_mul_f32_e32 v32, 0x3e38aa3b, v44
	v_add_f32_e32 v85, v90, v85
	v_add_f32_e32 v85, v91, v85
	v_exp_f32_e32 v44, v32
	v_mul_f32_e32 v32, 0x3e38aa3b, v45
	v_add_f32_e32 v85, v92, v85
	v_add_f32_e32 v85, v93, v85
	v_exp_f32_e32 v45, v32
	v_mul_f32_e32 v32, 0x3e38aa3b, v46
	v_cvt_pk_bf16_f32 v36, v40, v41
	v_add_f32_e32 v40, v40, v85
	v_add_f32_e32 v40, v41, v40
	v_exp_f32_e32 v46, v32
	v_add_f32_e32 v40, v42, v40
	v_add_f32_e32 v40, v43, v40
	v_add_f32_e32 v40, v44, v40
	v_add_f32_e32 v40, v45, v40
	v_cvt_pk_bf16_f32 v37, v42, v43
	v_cvt_pk_bf16_f32 v38, v44, v45
	v_add_f32_e32 v44, v46, v40
	ds_read2_b64 v[40:43], v81 offset0:16 offset1:18
	v_mul_f32_e32 v32, 0x3e38aa3b, v47
	v_exp_f32_e32 v47, v32
	v_cvt_pk_bf16_f32 v32, v86, v87
	v_cvt_pk_bf16_f32 v33, v88, v89
	v_cvt_pk_bf16_f32 v34, v90, v91
	v_cvt_pk_bf16_f32 v35, v92, v93
	v_cvt_pk_bf16_f32 v39, v46, v47
	ds_read_b128 v[86:89], v75 offset:13856
	s_waitcnt lgkmcnt(1)
	v_mfma_f32_32x32x16_bf16 v[0:15], v[40:43], v[32:35], v[0:15]
	ds_read2_b64 v[40:43], v81 offset0:20 offset1:22
	v_add_f32_e32 v85, v47, v44
	s_waitcnt lgkmcnt(0)
	v_mfma_f32_32x32x16_bf16 v[0:15], v[40:43], v[36:39], v[0:15]
	ds_read2_b64 v[40:43], v83 offset0:80 offset1:82
	s_waitcnt lgkmcnt(0)
	v_mfma_f32_32x32x16_bf16 v[16:31], v[40:43], v[32:35], v[16:31]
	ds_read2_b64 v[32:35], v83 offset0:84 offset1:86
	s_waitcnt lgkmcnt(0)
	v_mfma_f32_32x32x16_bf16 v[16:31], v[32:35], v[36:39], v[16:31]
	ds_read_b128 v[32:35], v75 offset:13824
	s_waitcnt lgkmcnt(0)
	v_mfma_f32_32x32x16_bf16 v[32:47], v[32:35], v[56:59], 0
	v_mfma_f32_32x32x16_bf16 v[32:47], v[86:89], v[48:51], v[32:47]
	ds_read_b128 v[86:89], v75 offset:13888
	s_waitcnt lgkmcnt(0)
	v_mfma_f32_32x32x16_bf16 v[32:47], v[86:89], v[52:55], v[32:47]
	ds_read_b128 v[86:89], v75 offset:13920
	s_waitcnt lgkmcnt(0)
	v_mfma_f32_32x32x16_bf16 v[32:47], v[86:89], v[60:63], v[32:47]
	s_nop 11
	v_mul_f32_e32 v32, 0x3e38aa3b, v32
	v_exp_f32_e32 v86, v32
	v_mul_f32_e32 v32, 0x3e38aa3b, v33
	v_exp_f32_e32 v87, v32
	v_mul_f32_e32 v32, 0x3e38aa3b, v34
	v_exp_f32_e32 v88, v32
	v_mul_f32_e32 v32, 0x3e38aa3b, v35
	v_exp_f32_e32 v89, v32
	v_mul_f32_e32 v32, 0x3e38aa3b, v36
	v_exp_f32_e32 v90, v32
	v_mul_f32_e32 v32, 0x3e38aa3b, v37
	v_exp_f32_e32 v91, v32
	v_mul_f32_e32 v32, 0x3e38aa3b, v38
	v_exp_f32_e32 v92, v32
	v_mul_f32_e32 v32, 0x3e38aa3b, v39
	v_exp_f32_e32 v93, v32
	v_mul_f32_e32 v32, 0x3e38aa3b, v40
	v_exp_f32_e32 v40, v32
	v_mul_f32_e32 v32, 0x3e38aa3b, v41
	v_exp_f32_e32 v41, v32
	v_mul_f32_e32 v32, 0x3e38aa3b, v42
	v_add_f32_e32 v85, v85, v86
	v_add_f32_e32 v85, v87, v85
	v_exp_f32_e32 v42, v32
	v_mul_f32_e32 v32, 0x3e38aa3b, v43
	v_add_f32_e32 v85, v88, v85
	v_add_f32_e32 v85, v89, v85
	v_exp_f32_e32 v43, v32
	v_mul_f32_e32 v32, 0x3e38aa3b, v44
	v_add_f32_e32 v85, v90, v85
	v_add_f32_e32 v85, v91, v85
	v_exp_f32_e32 v44, v32
	v_mul_f32_e32 v32, 0x3e38aa3b, v45
	v_add_f32_e32 v85, v92, v85
	v_add_f32_e32 v85, v93, v85
	v_exp_f32_e32 v45, v32
	v_mul_f32_e32 v32, 0x3e38aa3b, v46
	v_cvt_pk_bf16_f32 v36, v40, v41
	v_add_f32_e32 v40, v40, v85
	v_add_f32_e32 v40, v41, v40
	v_exp_f32_e32 v46, v32
	v_add_f32_e32 v40, v42, v40
	v_add_f32_e32 v40, v43, v40
	v_add_f32_e32 v40, v44, v40
	v_add_f32_e32 v40, v45, v40
	v_cvt_pk_bf16_f32 v37, v42, v43
	v_cvt_pk_bf16_f32 v38, v44, v45
	v_add_f32_e32 v44, v46, v40
	ds_read2_b64 v[40:43], v81 offset0:24 offset1:26
	v_mul_f32_e32 v32, 0x3e38aa3b, v47
	v_exp_f32_e32 v47, v32
	v_cvt_pk_bf16_f32 v32, v86, v87
	v_cvt_pk_bf16_f32 v33, v88, v89
	v_cvt_pk_bf16_f32 v34, v90, v91
	v_cvt_pk_bf16_f32 v35, v92, v93
	v_cvt_pk_bf16_f32 v39, v46, v47
	s_nop 0
	v_add_f32_e32 v85, v47, v44
	s_waitcnt lgkmcnt(0)
	v_mfma_f32_32x32x16_bf16 v[0:15], v[40:43], v[32:35], v[0:15]
	ds_read2_b64 v[40:43], v81 offset0:28 offset1:30
	s_waitcnt lgkmcnt(0)
	v_mfma_f32_32x32x16_bf16 v[0:15], v[40:43], v[36:39], v[0:15]
	ds_read2_b64 v[40:43], v83 offset0:88 offset1:90
	s_waitcnt lgkmcnt(0)
	v_mfma_f32_32x32x16_bf16 v[16:31], v[40:43], v[32:35], v[16:31]
	ds_read2_b64 v[32:35], v83 offset0:92 offset1:94
	s_waitcnt lgkmcnt(0)
	v_mfma_f32_32x32x16_bf16 v[16:31], v[32:35], v[36:39], v[16:31]
	s_cbranch_scc1 .LBB0_477
; __device__ __forceinline__ unsigned pack2(float a, float b) { unsigned r; asm("v_cvt_pk_bf16_f32 %0, %1, %2" : "=v"(r) : "v"(a), "v"(b)); return r; }
; #define layer launder_s(layer_)
; __device__ __forceinline__ void attn_item(const Params& p, int layer, bool isctx, int item, unsigned char* smem) {
;     ...
;   rsum += __shfl_xor(rsum, 32);
;   float denom = rsum + expf(p.in[21][layer * 8 + hq]);
;   float rinv = 1.0f / denom;
;   u16* YS = (u16*)(p.ws + O_YS) + (size_t)(qrow0 + ql) * 1536 + 512 + hq * 64;
; #pragma unroll
;   for (int mt = 0; mt < 2; mt++)
; #pragma unroll
;     for (int rq = 0; rq < 4; rq++) {
;       int d = mt * 32 + 8 * rq + 4 * hh;
;       uint2 o;
;       o.x = pack2(oacc[mt][rq * 4 + 0] * rinv, oacc[mt][rq * 4 + 1] * rinv);
;       o.y = pack2(oacc[mt][rq * 4 + 2] * rinv, oacc[mt][rq * 4 + 3] * rinv);
;       *(uint2*)(YS + d) = o;
;     }
	v_mov_b64_e32 v[32:33], s[6:7]
	global_load_dwordx2 v[34:35], v[32:33], off offset:168
	v_lshl_add_u32 v36, s10, 3, v65
	v_ashrrev_i32_e32 v37, 31, v36
	global_load_dwordx2 v[32:33], v[32:33], off offset:336
	v_cmp_lt_i32_e32 vcc, v236, v235
	v_readlane_b32 s6, v254, 42
	v_readlane_b32 s7, v254, 43
	s_add_i32 s5, s5, s6
	v_readlane_b32 s6, v254, 38
	s_add_i32 s4, s4, s6
	v_mov_b32_e32 v65, v161
	s_cmp_lt_i32 s5, 64
	s_waitcnt vmcnt(0) lgkmcnt(0)
	v_lshl_add_u64 v[34:35], v[36:37], 2, v[34:35]
	global_load_dword v36, v[34:35], off
	v_cndmask_b32_e32 v34, v234, v236, vcc
	v_lshlrev_b32_e32 v34, 2, v34
	ds_bpermute_b32 v34, v34, v85
	v_mad_i64_i32 v[32:33], s[6:7], v68, s69, v[32:33]
	v_lshl_add_u64 v[32:33], v[66:67], 1, v[32:33]
	v_lshl_add_u64 v[32:33], v[32:33], 0, v[64:65]
	s_waitcnt lgkmcnt(0)
	v_add_f32_e32 v37, v85, v34
	s_mov_b64 s[6:7], 0x1700c400
	s_waitcnt vmcnt(0)
	v_mul_f32_e32 v34, 0x3fb8aa3b, v36
	v_fma_f32 v35, v36, s55, -v34
	v_rndne_f32_e32 v38, v34
	v_fmac_f32_e32 v35, 0x32a5705f, v36
	v_sub_f32_e32 v34, v34, v38
	v_add_f32_e32 v34, v34, v35
	v_cvt_i32_f32_e32 v38, v38
	v_exp_f32_e32 v39, v34
	v_cmp_ngt_f32_e32 vcc, s56, v36
	v_lshl_add_u64 v[34:35], v[32:33], 0, s[6:7]
	v_ldexp_f32 v38, v39, v38
	v_cndmask_b32_e32 v38, 0, v38, vcc
	v_cmp_nlt_f32_e32 vcc, s54, v36
	s_nop 1
	v_cndmask_b32_e32 v36, v242, v38, vcc
	v_add_f32_e32 v36, v37, v36
	v_div_scale_f32 v37, s[6:7], v36, v36, 1.0
	v_rcp_f32_e32 v38, v37
	v_add_co_u32_e32 v32, vcc, s78, v32
	v_fma_f32 v40, -v37, v38, 1.0
	s_nop 0
	v_addc_co_u32_e32 v33, vcc, 0, v33, vcc
	v_div_scale_f32 v39, vcc, 1.0, v36, 1.0
	v_fmac_f32_e32 v38, v40, v38
	v_mul_f32_e32 v40, v39, v38
	v_fma_f32 v41, -v37, v40, v39
	v_fmac_f32_e32 v40, v41, v38
	v_fma_f32 v37, -v37, v40, v39
	v_div_fmas_f32 v37, v37, v38, v40
	v_div_fixup_f32 v36, v37, v36, 1.0
	v_mul_f32_e32 v0, v0, v36
	v_mul_f32_e32 v1, v1, v36
	v_mul_f32_e32 v2, v2, v36
	v_mul_f32_e32 v3, v3, v36
	v_mul_f32_e32 v4, v4, v36
	v_mul_f32_e32 v5, v5, v36
	v_mul_f32_e32 v6, v6, v36
	v_mul_f32_e32 v7, v7, v36
	v_mul_f32_e32 v8, v8, v36
	v_mul_f32_e32 v9, v9, v36
	v_mul_f32_e32 v10, v10, v36
	v_mul_f32_e32 v11, v11, v36
	v_mul_f32_e32 v12, v12, v36
	v_mul_f32_e32 v13, v13, v36
	v_mul_f32_e32 v14, v14, v36
	v_mul_f32_e32 v15, v15, v36
	v_cvt_pk_bf16_f32 v0, v0, v1
	v_cvt_pk_bf16_f32 v1, v2, v3
	v_mul_f32_e32 v16, v16, v36
	v_mul_f32_e32 v17, v17, v36
	v_mul_f32_e32 v18, v18, v36
	v_mul_f32_e32 v19, v19, v36
	v_mul_f32_e32 v20, v20, v36
	v_mul_f32_e32 v21, v21, v36
	v_mul_f32_e32 v22, v22, v36
	v_mul_f32_e32 v23, v23, v36
	v_mul_f32_e32 v24, v24, v36
	v_mul_f32_e32 v25, v25, v36
	v_mul_f32_e32 v26, v26, v36
	v_mul_f32_e32 v27, v27, v36
	v_mul_f32_e32 v28, v28, v36
	v_mul_f32_e32 v29, v29, v36
	v_mul_f32_e32 v30, v30, v36
	v_mul_f32_e32 v31, v31, v36
	v_cvt_pk_bf16_f32 v2, v4, v5
	v_cvt_pk_bf16_f32 v3, v6, v7
	v_cvt_pk_bf16_f32 v4, v8, v9
	v_cvt_pk_bf16_f32 v5, v10, v11
	v_cvt_pk_bf16_f32 v6, v12, v13
	v_cvt_pk_bf16_f32 v7, v14, v15
	v_cvt_pk_bf16_f32 v8, v16, v17
	v_cvt_pk_bf16_f32 v9, v18, v19
	v_cvt_pk_bf16_f32 v10, v20, v21
	v_cvt_pk_bf16_f32 v11, v22, v23
	v_cvt_pk_bf16_f32 v12, v24, v25
	v_cvt_pk_bf16_f32 v13, v26, v27
	v_cvt_pk_bf16_f32 v14, v28, v29
	v_cvt_pk_bf16_f32 v15, v30, v31
	global_store_dwordx2 v[32:33], v[0:1], off offset:1024
	global_store_dwordx2 v[34:35], v[2:3], off offset:16
	global_store_dwordx2 v[34:35], v[4:5], off offset:32
	global_store_dwordx2 v[34:35], v[6:7], off offset:48
	global_store_dwordx2 v[34:35], v[8:9], off offset:64
	global_store_dwordx2 v[34:35], v[10:11], off offset:80
	global_store_dwordx2 v[34:35], v[12:13], off offset:96
	global_store_dwordx2 v[34:35], v[14:15], off offset:112
	s_waitcnt lgkmcnt(0)
	s_barrier
	s_cbranch_scc1 .LBB0_476

; __device__ __forceinline__ void attn_item(const Params& p, int layer, bool isctx, int item, unsigned char* smem) {
;     ...
;     __syncthreads();
; #pragma unroll
;     for (int i = 0; i < 2; i++) {
;       int e = tid + NT * i;
;       int r = e >> 3, cch = (e & 7) * 8;
;       *(uint4*)(Ks + r * 72 + cch) = *(const uint4*)(KR + (size_t)(krow0 + r) * 128 + kvh * 64 + cch);
;       int d = e >> 4, kc = (e & 15) * 8;
;       *(uint4*)(Vt + d * 136 + kc) = *(const uint4*)(VT + (size_t)(kvh * 64 + d) * TA + krow0 + kc);
;     }
;     __syncthreads();
; #pragma unroll
;     for (int k4 = 0; k4 < 4; k4++) {
;       f32x16 st;
; #pragma unroll
;       for (int r = 0; r < 16; r++) st[r] = 0.f;
; #pragma unroll
;       for (int ks = 0; ks < 4; ks++) {
;         bf16x8 kf = *(const bf16x8*)(Ks + (k4 * 32 + (lane & 31)) * 72 + ks * 16 + hh * 8);
;         st = __builtin_amdgcn_mfma_f32_32x32x16_bf16(kf, qf[ks], st, 0, 0, 0);
;       }
;       float pe[16];
; #pragma unroll
;       for (int r = 0; r < 16; r++) {
;         int kl = k4 * 32 + (r & 3) + 8 * (r >> 2) + 4 * hh;
;         float e = __expf(st[r] * 0.125f);
;         bool valid = (mtype * kl) <= mq;
;         e = valid ? e : 0.f;
;         pe[r] = e; rsum += e;
;       }
.LBB0_488:
	v_add_u32_e32 v32, s8, v82
	v_ashrrev_i32_e32 v33, 31, v32
	v_lshlrev_b64 v[32:33], 8, v[32:33]
	v_lshl_add_u64 v[32:33], v[68:69], 0, v[32:33]
	s_waitcnt lgkmcnt(0)
	s_barrier
	global_load_dwordx4 v[40:43], v[32:33], off
	s_ashr_i32 s9, s8, 31
	v_lshl_add_u64 v[36:37], s[8:9], 1, v[70:71]
	v_mul_lo_u32 v88, s19, v81
	v_mul_lo_u32 v87, s19, v67
	v_cmp_le_i32_e32 vcc, v87, v88
	v_lshl_add_u64 v[32:33], v[36:37], 0, v[74:75]
	global_load_dwordx4 v[44:47], v[32:33], off
	v_add_u32_e32 v32, s8, v83
	v_ashrrev_i32_e32 v33, 31, v32
	v_lshlrev_b64 v[32:33], 8, v[32:33]
	v_lshl_add_u64 v[32:33], v[68:69], 0, v[32:33]
	global_load_dwordx4 v[90:93], v[32:33], off
	v_lshl_add_u64 v[32:33], v[36:37], 0, v[78:79]
	global_load_dwordx4 v[32:35], v[32:33], off
	s_mul_i32 s8, s19, 5
	s_waitcnt vmcnt(3)
	ds_write_b128 v72, v[40:43]
	s_waitcnt vmcnt(2)
	ds_write_b128 v73, v[44:47]
	s_waitcnt vmcnt(1)
	ds_write_b128 v76, v[90:93]
	s_waitcnt vmcnt(0)
	ds_write_b128 v77, v[32:35]
	s_waitcnt lgkmcnt(0)
	s_barrier
	ds_read_b128 v[32:35], v84
	ds_read_b128 v[90:93], v84 offset:32
	s_waitcnt lgkmcnt(1)
	v_mfma_f32_32x32x16_bf16 v[32:47], v[32:35], v[56:59], 0
	s_waitcnt lgkmcnt(0)
	v_mfma_f32_32x32x16_bf16 v[32:47], v[90:93], v[48:51], v[32:47]
	ds_read_b128 v[90:93], v84 offset:64
	s_waitcnt lgkmcnt(0)
	v_mfma_f32_32x32x16_bf16 v[32:47], v[90:93], v[52:55], v[32:47]
	ds_read_b128 v[90:93], v84 offset:96
	s_waitcnt lgkmcnt(0)
	v_mfma_f32_32x32x16_bf16 v[32:47], v[90:93], v[60:63], v[32:47]
	s_nop 11
	v_mul_f32_e32 v32, 0x3e38aa3b, v32
	v_exp_f32_e32 v32, v32
	s_nop 0
	v_cndmask_b32_e32 v89, 0, v32, vcc
	v_mul_f32_e32 v32, 0x3e38aa3b, v33
	v_exp_f32_e32 v32, v32
	v_add_u32_e32 v33, s19, v87
	v_cmp_le_i32_e32 vcc, v33, v88
	v_add_u32_e32 v33, s19, v33
	s_nop 0
	v_cndmask_b32_e32 v87, 0, v32, vcc
	v_mul_f32_e32 v32, 0x3e38aa3b, v34
	v_exp_f32_e32 v32, v32
	v_cmp_le_i32_e32 vcc, v33, v88
	v_add_u32_e32 v33, s19, v33
	s_nop 0
	v_cndmask_b32_e32 v90, 0, v32, vcc
	v_mul_f32_e32 v32, 0x3e38aa3b, v35
	v_exp_f32_e32 v32, v32
	v_cmp_le_i32_e32 vcc, v33, v88
	v_add_u32_e32 v33, s8, v33
	s_nop 0
	v_cndmask_b32_e32 v91, 0, v32, vcc
	v_mul_f32_e32 v32, 0x3e38aa3b, v36
	v_exp_f32_e32 v32, v32
	v_cmp_le_i32_e32 vcc, v33, v88
	v_add_u32_e32 v33, s19, v33
	s_nop 0
	v_cndmask_b32_e32 v92, 0, v32, vcc
	v_mul_f32_e32 v32, 0x3e38aa3b, v37
	v_exp_f32_e32 v32, v32
	v_cmp_le_i32_e32 vcc, v33, v88
	v_add_u32_e32 v33, s19, v33
	s_nop 0
	v_cndmask_b32_e32 v93, 0, v32, vcc
	v_mul_f32_e32 v32, 0x3e38aa3b, v38
	v_exp_f32_e32 v32, v32
	v_cmp_le_i32_e32 vcc, v33, v88
	v_add_u32_e32 v33, s19, v33
	v_cvt_pk_bf16_f32 v34, v92, v93
	s_nop 0
	v_cndmask_b32_e32 v94, 0, v32, vcc
	v_mul_f32_e32 v32, 0x3e38aa3b, v39
	v_exp_f32_e32 v32, v32
	v_cmp_le_i32_e32 vcc, v33, v88
	v_add_u32_e32 v33, s8, v33
	s_nop 0
	v_cndmask_b32_e32 v95, 0, v32, vcc
	v_mul_f32_e32 v32, 0x3e38aa3b, v40
	v_exp_f32_e32 v32, v32
	v_cmp_le_i32_e32 vcc, v33, v88
	v_add_u32_e32 v33, s19, v33
	v_cvt_pk_bf16_f32 v35, v94, v95
	s_nop 0
	v_cndmask_b32_e32 v40, 0, v32, vcc
	v_mul_f32_e32 v32, 0x3e38aa3b, v41
	v_exp_f32_e32 v32, v32
	v_cmp_le_i32_e32 vcc, v33, v88
	v_add_u32_e32 v33, s19, v33
	s_nop 0
	v_cndmask_b32_e32 v41, 0, v32, vcc
	v_mul_f32_e32 v32, 0x3e38aa3b, v42
	v_exp_f32_e32 v32, v32
	v_cmp_le_i32_e32 vcc, v33, v88
	v_add_u32_e32 v33, s19, v33
	v_cvt_pk_bf16_f32 v36, v40, v41
	s_nop 0
	v_cndmask_b32_e32 v42, 0, v32, vcc
	v_mul_f32_e32 v32, 0x3e38aa3b, v43
	v_exp_f32_e32 v32, v32
	v_cmp_le_i32_e32 vcc, v33, v88
	v_add_u32_e32 v33, s8, v33
	s_nop 0
	v_cndmask_b32_e32 v43, 0, v32, vcc
	v_mul_f32_e32 v32, 0x3e38aa3b, v44
	v_exp_f32_e32 v32, v32
	v_cmp_le_i32_e32 vcc, v33, v88
	v_add_u32_e32 v33, s19, v33
	v_cvt_pk_bf16_f32 v37, v42, v43
	s_nop 0
	v_cndmask_b32_e32 v44, 0, v32, vcc
	v_mul_f32_e32 v32, 0x3e38aa3b, v45
	v_exp_f32_e32 v32, v32
	v_cmp_le_i32_e32 vcc, v33, v88
	v_add_u32_e32 v33, s19, v33
	v_add_u32_e32 v96, s19, v33
	v_cndmask_b32_e32 v45, 0, v32, vcc
	v_mul_f32_e32 v32, 0x3e38aa3b, v46
	v_exp_f32_e32 v32, v32
	v_cmp_le_i32_e32 vcc, v33, v88
	v_cvt_pk_bf16_f32 v38, v44, v45
	v_cvt_pk_bf16_f32 v33, v90, v91
	s_nop 1
	v_cndmask_b32_e32 v46, 0, v32, vcc
	v_mul_f32_e32 v32, 0x3e38aa3b, v47
	v_add_f32_e32 v47, v86, v89
	v_add_f32_e32 v47, v87, v47
	v_add_f32_e32 v47, v90, v47
	v_add_f32_e32 v47, v91, v47
	v_add_f32_e32 v47, v92, v47
	v_add_f32_e32 v47, v93, v47
	v_add_f32_e32 v47, v94, v47
	v_add_f32_e32 v47, v95, v47
	v_add_f32_e32 v40, v40, v47
	v_exp_f32_e32 v32, v32
	v_add_f32_e32 v40, v41, v40
	v_add_f32_e32 v40, v42, v40
	v_add_f32_e32 v40, v43, v40
	v_cmp_le_i32_e32 vcc, v96, v88
	v_add_f32_e32 v40, v44, v40
	v_add_f32_e32 v40, v45, v40
	v_cndmask_b32_e32 v97, 0, v32, vcc
	v_cvt_pk_bf16_f32 v32, v89, v87
	v_add_u32_e32 v87, 0x4800, v85
	v_cvt_pk_bf16_f32 v39, v46, v97
	v_add_f32_e32 v89, v46, v40
	ds_read2_b64 v[40:43], v87 offset1:2
	ds_read2_b64 v[44:47], v87 offset0:4 offset1:6
	v_add_u32_e32 v86, 0x6800, v85
	s_waitcnt lgkmcnt(1)
	v_mfma_f32_32x32x16_bf16 v[16:31], v[40:43], v[32:35], v[16:31]
	ds_read2_b64 v[40:43], v86 offset0:64 offset1:66
	ds_read_b128 v[92:95], v84 offset:4640
	v_add_f32_e32 v90, v97, v89
	v_add_u32_e32 v89, s8, v96
	v_cmp_le_i32_e32 vcc, v89, v88
	s_waitcnt lgkmcnt(1)
	v_mfma_f32_32x32x16_bf16 v[0:15], v[40:43], v[32:35], v[0:15]
	ds_read2_b64 v[32:35], v86 offset0:68 offset1:70
	s_waitcnt lgkmcnt(0)
	v_mfma_f32_32x32x16_bf16 v[0:15], v[32:35], v[36:39], v[0:15]
	ds_read_b128 v[32:35], v84 offset:4608
	v_mfma_f32_32x32x16_bf16 v[16:31], v[44:47], v[36:39], v[16:31]
	s_waitcnt lgkmcnt(0)
	v_mfma_f32_32x32x16_bf16 v[32:47], v[32:35], v[56:59], 0
	v_mfma_f32_32x32x16_bf16 v[32:47], v[92:95], v[48:51], v[32:47]
	ds_read_b128 v[92:95], v84 offset:4672
	s_waitcnt lgkmcnt(0)
; __device__ __forceinline__ unsigned pack2(float a, float b) { unsigned r; asm("v_cvt_pk_bf16_f32 %0, %1, %2" : "=v"(r) : "v"(a), "v"(b)); return r; }
; __device__ __forceinline__ void attn_item(const Params& p, int layer, bool isctx, int item, unsigned char* smem) {
;     ...
; #pragma unroll
;     for (int k4 = 0; k4 < 4; k4++) {
;       f32x16 st;
; #pragma unroll
;       for (int r = 0; r < 16; r++) st[r] = 0.f;
; #pragma unroll
;       for (int ks = 0; ks < 4; ks++) {
;         bf16x8 kf = *(const bf16x8*)(Ks + (k4 * 32 + (lane & 31)) * 72 + ks * 16 + hh * 8);
;         st = __builtin_amdgcn_mfma_f32_32x32x16_bf16(kf, qf[ks], st, 0, 0, 0);
;       }
;       float pe[16];
; #pragma unroll
;       for (int r = 0; r < 16; r++) {
;         int kl = k4 * 32 + (r & 3) + 8 * (r >> 2) + 4 * hh;
;         float e = __expf(st[r] * 0.125f);
;         bool valid = (mtype * kl) <= mq;
;         e = valid ? e : 0.f;
;         pe[r] = e; rsum += e;
;       }
;       bf16x8 pb[2];
; #pragma unroll
;       for (int s = 0; s < 2; s++) {
;         union { bf16x8 v; unsigned w[4]; } cv;
; #pragma unroll
;         for (int q = 0; q < 4; q++) cv.w[q] = pack2(pe[8 * s + 2 * q], pe[8 * s + 2 * q + 1]);
;         pb[s] = cv.v;
;       }
; #pragma unroll
;       for (int mt = 0; mt < 2; mt++)
; #pragma unroll
;         for (int s = 0; s < 2; s++) {
;           const u16* vp = Vt + (mt * 32 + (lane & 31)) * 136 + k4 * 32 + 16 * s + 4 * hh;
;           union { bf16x8 v; uint2 h2[2]; } av;
;           av.h2[0] = *(const uint2*)vp;
;           av.h2[1] = *(const uint2*)(vp + 8);
;           oacc[mt] = __builtin_amdgcn_mfma_f32_32x32x16_bf16(av.v, pb[s], oacc[mt], 0, 0, 0);
;         }
	v_mfma_f32_32x32x16_bf16 v[32:47], v[92:95], v[52:55], v[32:47]
	ds_read_b128 v[92:95], v84 offset:4704
	s_waitcnt lgkmcnt(0)
	v_mfma_f32_32x32x16_bf16 v[32:47], v[92:95], v[60:63], v[32:47]
	s_nop 11
	v_mul_f32_e32 v32, 0x3e38aa3b, v32
	v_exp_f32_e32 v32, v32
	s_nop 0
	v_cndmask_b32_e32 v91, 0, v32, vcc
	v_mul_f32_e32 v32, 0x3e38aa3b, v33
	v_exp_f32_e32 v32, v32
	v_add_u32_e32 v33, s19, v89
	v_cmp_le_i32_e32 vcc, v33, v88
	v_add_u32_e32 v33, s19, v33
	v_add_f32_e32 v90, v90, v91
	v_cndmask_b32_e32 v92, 0, v32, vcc
	v_mul_f32_e32 v32, 0x3e38aa3b, v34
	v_exp_f32_e32 v32, v32
	v_cmp_le_i32_e32 vcc, v33, v88
	v_add_u32_e32 v33, s19, v33
	v_add_f32_e32 v90, v92, v90
	v_cndmask_b32_e32 v93, 0, v32, vcc
	v_mul_f32_e32 v32, 0x3e38aa3b, v35
	v_exp_f32_e32 v32, v32
	v_cmp_le_i32_e32 vcc, v33, v88
	v_add_u32_e32 v33, s8, v33
	v_add_f32_e32 v90, v93, v90
	v_cndmask_b32_e32 v94, 0, v32, vcc
	v_mul_f32_e32 v32, 0x3e38aa3b, v36
	v_exp_f32_e32 v32, v32
	v_cmp_le_i32_e32 vcc, v33, v88
	v_add_u32_e32 v33, s19, v33
	v_add_f32_e32 v90, v94, v90
	v_cndmask_b32_e32 v95, 0, v32, vcc
	v_mul_f32_e32 v32, 0x3e38aa3b, v37
	v_exp_f32_e32 v32, v32
	v_cmp_le_i32_e32 vcc, v33, v88
	v_add_u32_e32 v33, s19, v33
	v_add_f32_e32 v90, v95, v90
	v_cndmask_b32_e32 v96, 0, v32, vcc
	v_mul_f32_e32 v32, 0x3e38aa3b, v38
	v_exp_f32_e32 v32, v32
	v_cmp_le_i32_e32 vcc, v33, v88
	v_add_u32_e32 v33, s19, v33
	v_add_f32_e32 v90, v96, v90
	v_cndmask_b32_e32 v97, 0, v32, vcc
	v_mul_f32_e32 v32, 0x3e38aa3b, v39
	v_exp_f32_e32 v32, v32
	v_cmp_le_i32_e32 vcc, v33, v88
	v_add_u32_e32 v33, s8, v33
	v_add_f32_e32 v90, v97, v90
	v_cndmask_b32_e32 v98, 0, v32, vcc
	v_mul_f32_e32 v32, 0x3e38aa3b, v40
	v_exp_f32_e32 v32, v32
	v_cmp_le_i32_e32 vcc, v33, v88
	v_add_u32_e32 v33, s19, v33
	v_add_f32_e32 v90, v98, v90
	v_cndmask_b32_e32 v40, 0, v32, vcc
	v_mul_f32_e32 v32, 0x3e38aa3b, v41
	v_exp_f32_e32 v32, v32
	v_cmp_le_i32_e32 vcc, v33, v88
	v_add_u32_e32 v33, s19, v33
	v_cvt_pk_bf16_f32 v34, v95, v96
	v_cvt_pk_bf16_f32 v35, v97, v98
	s_nop 0
	v_cndmask_b32_e32 v41, 0, v32, vcc
	v_mul_f32_e32 v32, 0x3e38aa3b, v42
	v_exp_f32_e32 v32, v32
	v_cmp_le_i32_e32 vcc, v33, v88
	v_add_u32_e32 v33, s19, v33
	v_cvt_pk_bf16_f32 v36, v40, v41
	v_add_f32_e32 v40, v40, v90
	v_cndmask_b32_e32 v42, 0, v32, vcc
	v_mul_f32_e32 v32, 0x3e38aa3b, v43
	v_exp_f32_e32 v32, v32
	v_cmp_le_i32_e32 vcc, v33, v88
	v_add_u32_e32 v33, s8, v33
	v_add_f32_e32 v40, v41, v40
	v_cndmask_b32_e32 v43, 0, v32, vcc
	v_mul_f32_e32 v32, 0x3e38aa3b, v44
	v_exp_f32_e32 v32, v32
	v_cmp_le_i32_e32 vcc, v33, v88
	v_add_u32_e32 v33, s19, v33
	v_add_f32_e32 v40, v42, v40
	v_cndmask_b32_e32 v44, 0, v32, vcc
	v_mul_f32_e32 v32, 0x3e38aa3b, v45
	v_exp_f32_e32 v32, v32
	v_cmp_le_i32_e32 vcc, v33, v88
	v_add_u32_e32 v33, s19, v33
	v_add_f32_e32 v40, v43, v40
	v_cndmask_b32_e32 v45, 0, v32, vcc
	v_mul_f32_e32 v32, 0x3e38aa3b, v46
	v_exp_f32_e32 v32, v32
	v_cmp_le_i32_e32 vcc, v33, v88
	v_add_f32_e32 v40, v44, v40
	v_add_f32_e32 v40, v45, v40
	v_cndmask_b32_e32 v46, 0, v32, vcc
	v_cvt_pk_bf16_f32 v37, v42, v43
	v_cvt_pk_bf16_f32 v38, v44, v45
	v_add_f32_e32 v44, v46, v40
	ds_read2_b64 v[40:43], v87 offset0:8 offset1:10
	v_mul_f32_e32 v32, 0x3e38aa3b, v47
	v_exp_f32_e32 v32, v32
	v_add_u32_e32 v89, s19, v33
	v_cmp_le_i32_e32 vcc, v89, v88
	v_cvt_pk_bf16_f32 v33, v93, v94
	v_add_u32_e32 v89, s8, v89
	s_nop 0
	v_cndmask_b32_e32 v47, 0, v32, vcc
	v_cvt_pk_bf16_f32 v32, v91, v92
	v_cvt_pk_bf16_f32 v39, v46, v47
	ds_read_b128 v[92:95], v84 offset:9248
	s_waitcnt lgkmcnt(1)
	v_mfma_f32_32x32x16_bf16 v[16:31], v[40:43], v[32:35], v[16:31]
	ds_read2_b64 v[40:43], v87 offset0:12 offset1:14
	v_add_f32_e32 v90, v47, v44
	v_cmp_le_i32_e32 vcc, v89, v88
	s_waitcnt lgkmcnt(0)
	v_mfma_f32_32x32x16_bf16 v[16:31], v[40:43], v[36:39], v[16:31]
	ds_read2_b64 v[40:43], v86 offset0:72 offset1:74
	s_waitcnt lgkmcnt(0)
	v_mfma_f32_32x32x16_bf16 v[0:15], v[40:43], v[32:35], v[0:15]
	ds_read2_b64 v[32:35], v86 offset0:76 offset1:78
	s_waitcnt lgkmcnt(0)
	v_mfma_f32_32x32x16_bf16 v[0:15], v[32:35], v[36:39], v[0:15]
	ds_read_b128 v[32:35], v84 offset:9216
	s_waitcnt lgkmcnt(0)
	v_mfma_f32_32x32x16_bf16 v[32:47], v[32:35], v[56:59], 0
	v_mfma_f32_32x32x16_bf16 v[32:47], v[92:95], v[48:51], v[32:47]
	ds_read_b128 v[92:95], v84 offset:9280
	s_waitcnt lgkmcnt(0)
	v_mfma_f32_32x32x16_bf16 v[32:47], v[92:95], v[52:55], v[32:47]
	ds_read_b128 v[92:95], v84 offset:9312
	s_waitcnt lgkmcnt(0)
; __device__ __forceinline__ unsigned pack2(float a, float b) { unsigned r; asm("v_cvt_pk_bf16_f32 %0, %1, %2" : "=v"(r) : "v"(a), "v"(b)); return r; }
; __device__ __forceinline__ void attn_item(const Params& p, int layer, bool isctx, int item, unsigned char* smem) {
;     ...
; #pragma unroll
;     for (int k4 = 0; k4 < 4; k4++) {
;       f32x16 st;
; #pragma unroll
;       for (int r = 0; r < 16; r++) st[r] = 0.f;
; #pragma unroll
;       for (int ks = 0; ks < 4; ks++) {
;         bf16x8 kf = *(const bf16x8*)(Ks + (k4 * 32 + (lane & 31)) * 72 + ks * 16 + hh * 8);
;         st = __builtin_amdgcn_mfma_f32_32x32x16_bf16(kf, qf[ks], st, 0, 0, 0);
;       }
;       float pe[16];
; #pragma unroll
;       for (int r = 0; r < 16; r++) {
;         int kl = k4 * 32 + (r & 3) + 8 * (r >> 2) + 4 * hh;
;         float e = __expf(st[r] * 0.125f);
;         bool valid = (mtype * kl) <= mq;
;         e = valid ? e : 0.f;
;         pe[r] = e; rsum += e;
;       }
;       bf16x8 pb[2];
; #pragma unroll
;       for (int s = 0; s < 2; s++) {
;         union { bf16x8 v; unsigned w[4]; } cv;
; #pragma unroll
;         for (int q = 0; q < 4; q++) cv.w[q] = pack2(pe[8 * s + 2 * q], pe[8 * s + 2 * q + 1]);
;         pb[s] = cv.v;
;       }
; #pragma unroll
;       for (int mt = 0; mt < 2; mt++)
; #pragma unroll
;         for (int s = 0; s < 2; s++) {
;           const u16* vp = Vt + (mt * 32 + (lane & 31)) * 136 + k4 * 32 + 16 * s + 4 * hh;
;           union { bf16x8 v; uint2 h2[2]; } av;
;           av.h2[0] = *(const uint2*)vp;
;           av.h2[1] = *(const uint2*)(vp + 8);
;           oacc[mt] = __builtin_amdgcn_mfma_f32_32x32x16_bf16(av.v, pb[s], oacc[mt], 0, 0, 0);
;         }
	v_mfma_f32_32x32x16_bf16 v[32:47], v[92:95], v[60:63], v[32:47]
	s_nop 11
	v_mul_f32_e32 v32, 0x3e38aa3b, v32
	v_exp_f32_e32 v32, v32
	s_nop 0
	v_cndmask_b32_e32 v91, 0, v32, vcc
	v_mul_f32_e32 v32, 0x3e38aa3b, v33
	v_exp_f32_e32 v32, v32
	v_add_u32_e32 v33, s19, v89
	v_cmp_le_i32_e32 vcc, v33, v88
	v_add_u32_e32 v33, s19, v33
	v_add_f32_e32 v90, v90, v91
	v_cndmask_b32_e32 v92, 0, v32, vcc
	v_mul_f32_e32 v32, 0x3e38aa3b, v34
	v_exp_f32_e32 v32, v32
	v_cmp_le_i32_e32 vcc, v33, v88
	v_add_u32_e32 v33, s19, v33
	v_add_f32_e32 v90, v92, v90
	v_cndmask_b32_e32 v93, 0, v32, vcc
	v_mul_f32_e32 v32, 0x3e38aa3b, v35
	v_exp_f32_e32 v32, v32
	v_cmp_le_i32_e32 vcc, v33, v88
	v_add_u32_e32 v33, s8, v33
	v_add_f32_e32 v90, v93, v90
	v_cndmask_b32_e32 v94, 0, v32, vcc
	v_mul_f32_e32 v32, 0x3e38aa3b, v36
	v_exp_f32_e32 v32, v32
	v_cmp_le_i32_e32 vcc, v33, v88
	v_add_u32_e32 v33, s19, v33
	v_add_f32_e32 v90, v94, v90
	v_cndmask_b32_e32 v95, 0, v32, vcc
	v_mul_f32_e32 v32, 0x3e38aa3b, v37
	v_exp_f32_e32 v32, v32
	v_cmp_le_i32_e32 vcc, v33, v88
	v_add_u32_e32 v33, s19, v33
	v_add_f32_e32 v90, v95, v90
	v_cndmask_b32_e32 v96, 0, v32, vcc
	v_mul_f32_e32 v32, 0x3e38aa3b, v38
	v_exp_f32_e32 v32, v32
	v_cmp_le_i32_e32 vcc, v33, v88
	v_add_u32_e32 v33, s19, v33
	v_add_f32_e32 v90, v96, v90
	v_cndmask_b32_e32 v97, 0, v32, vcc
	v_mul_f32_e32 v32, 0x3e38aa3b, v39
	v_exp_f32_e32 v32, v32
	v_cmp_le_i32_e32 vcc, v33, v88
	v_add_u32_e32 v33, s8, v33
	v_add_f32_e32 v90, v97, v90
	v_cndmask_b32_e32 v98, 0, v32, vcc
	v_mul_f32_e32 v32, 0x3e38aa3b, v40
	v_exp_f32_e32 v32, v32
	v_cmp_le_i32_e32 vcc, v33, v88
	v_add_u32_e32 v33, s19, v33
	v_add_f32_e32 v90, v98, v90
	v_cndmask_b32_e32 v40, 0, v32, vcc
	v_mul_f32_e32 v32, 0x3e38aa3b, v41
	v_exp_f32_e32 v32, v32
	v_cmp_le_i32_e32 vcc, v33, v88
	v_add_u32_e32 v33, s19, v33
	v_cvt_pk_bf16_f32 v34, v95, v96
	v_cvt_pk_bf16_f32 v35, v97, v98
	s_nop 0
	v_cndmask_b32_e32 v41, 0, v32, vcc
	v_mul_f32_e32 v32, 0x3e38aa3b, v42
	v_exp_f32_e32 v32, v32
	v_cmp_le_i32_e32 vcc, v33, v88
	v_add_u32_e32 v33, s19, v33
	v_cvt_pk_bf16_f32 v36, v40, v41
	v_add_f32_e32 v40, v40, v90
	v_cndmask_b32_e32 v42, 0, v32, vcc
	v_mul_f32_e32 v32, 0x3e38aa3b, v43
	v_exp_f32_e32 v32, v32
	v_cmp_le_i32_e32 vcc, v33, v88
	v_add_u32_e32 v33, s8, v33
	v_add_f32_e32 v40, v41, v40
	v_cndmask_b32_e32 v43, 0, v32, vcc
	v_mul_f32_e32 v32, 0x3e38aa3b, v44
	v_exp_f32_e32 v32, v32
	v_cmp_le_i32_e32 vcc, v33, v88
	v_add_u32_e32 v33, s19, v33
	v_add_f32_e32 v40, v42, v40
	v_cndmask_b32_e32 v44, 0, v32, vcc
	v_mul_f32_e32 v32, 0x3e38aa3b, v45
	v_exp_f32_e32 v32, v32
	v_cmp_le_i32_e32 vcc, v33, v88
	v_add_u32_e32 v33, s19, v33
	v_add_f32_e32 v40, v43, v40
	v_cndmask_b32_e32 v45, 0, v32, vcc
	v_mul_f32_e32 v32, 0x3e38aa3b, v46
	v_exp_f32_e32 v32, v32
	v_cmp_le_i32_e32 vcc, v33, v88
	v_add_f32_e32 v40, v44, v40
	v_add_f32_e32 v40, v45, v40
	v_cndmask_b32_e32 v46, 0, v32, vcc
	v_cvt_pk_bf16_f32 v37, v42, v43
	v_cvt_pk_bf16_f32 v38, v44, v45
	v_add_f32_e32 v44, v46, v40
	ds_read2_b64 v[40:43], v87 offset0:16 offset1:18
	v_mul_f32_e32 v32, 0x3e38aa3b, v47
	v_exp_f32_e32 v32, v32
	v_add_u32_e32 v89, s19, v33
	v_cmp_le_i32_e32 vcc, v89, v88
	v_cvt_pk_bf16_f32 v33, v93, v94
	v_add_u32_e32 v89, s8, v89
	s_nop 0
	v_cndmask_b32_e32 v47, 0, v32, vcc
	v_cvt_pk_bf16_f32 v32, v91, v92
	v_cvt_pk_bf16_f32 v39, v46, v47
	ds_read_b128 v[92:95], v84 offset:13856
	s_waitcnt lgkmcnt(1)
	v_mfma_f32_32x32x16_bf16 v[16:31], v[40:43], v[32:35], v[16:31]
	ds_read2_b64 v[40:43], v87 offset0:20 offset1:22
	v_add_f32_e32 v90, v47, v44
	v_cmp_le_i32_e32 vcc, v89, v88
	s_waitcnt lgkmcnt(0)
	v_mfma_f32_32x32x16_bf16 v[16:31], v[40:43], v[36:39], v[16:31]
	ds_read2_b64 v[40:43], v86 offset0:80 offset1:82
	s_waitcnt lgkmcnt(0)
	v_mfma_f32_32x32x16_bf16 v[0:15], v[40:43], v[32:35], v[0:15]
	ds_read2_b64 v[32:35], v86 offset0:84 offset1:86
	s_waitcnt lgkmcnt(0)
	v_mfma_f32_32x32x16_bf16 v[0:15], v[32:35], v[36:39], v[0:15]
	ds_read_b128 v[32:35], v84 offset:13824
	s_waitcnt lgkmcnt(0)
	v_mfma_f32_32x32x16_bf16 v[32:47], v[32:35], v[56:59], 0
	v_mfma_f32_32x32x16_bf16 v[32:47], v[92:95], v[48:51], v[32:47]
	ds_read_b128 v[92:95], v84 offset:13888
	s_waitcnt lgkmcnt(0)
; __device__ __forceinline__ unsigned pack2(float a, float b) { unsigned r; asm("v_cvt_pk_bf16_f32 %0, %1, %2" : "=v"(r) : "v"(a), "v"(b)); return r; }
; __device__ __forceinline__ void attn_item(const Params& p, int layer, bool isctx, int item, unsigned char* smem) {
;     ...
;       for (int r = 0; r < 16; r++) {
;         int kl = k4 * 32 + (r & 3) + 8 * (r >> 2) + 4 * hh;
;         float e = __expf(st[r] * 0.125f);
;         bool valid = (mtype * kl) <= mq;
;         e = valid ? e : 0.f;
;         pe[r] = e; rsum += e;
;       }
;       bf16x8 pb[2];
; #pragma unroll
;       for (int s = 0; s < 2; s++) {
;         union { bf16x8 v; unsigned w[4]; } cv;
; #pragma unroll
;         for (int q = 0; q < 4; q++) cv.w[q] = pack2(pe[8 * s + 2 * q], pe[8 * s + 2 * q + 1]);
;         pb[s] = cv.v;
;       }
; #pragma unroll
;       for (int mt = 0; mt < 2; mt++)
; #pragma unroll
;         for (int s = 0; s < 2; s++) {
;           const u16* vp = Vt + (mt * 32 + (lane & 31)) * 136 + k4 * 32 + 16 * s + 4 * hh;
;           union { bf16x8 v; uint2 h2[2]; } av;
;           av.h2[0] = *(const uint2*)vp;
;           av.h2[1] = *(const uint2*)(vp + 8);
;           oacc[mt] = __builtin_amdgcn_mfma_f32_32x32x16_bf16(av.v, pb[s], oacc[mt], 0, 0, 0);
	v_mfma_f32_32x32x16_bf16 v[32:47], v[92:95], v[52:55], v[32:47]
	ds_read_b128 v[92:95], v84 offset:13920
	s_waitcnt lgkmcnt(0)
	v_mfma_f32_32x32x16_bf16 v[32:47], v[92:95], v[60:63], v[32:47]
	s_nop 11
	v_mul_f32_e32 v32, 0x3e38aa3b, v32
	v_exp_f32_e32 v32, v32
	s_nop 0
	v_cndmask_b32_e32 v91, 0, v32, vcc
	v_mul_f32_e32 v32, 0x3e38aa3b, v33
	v_exp_f32_e32 v32, v32
	v_add_u32_e32 v33, s19, v89
	v_cmp_le_i32_e32 vcc, v33, v88
	v_add_u32_e32 v33, s19, v33
	s_nop 0
	v_cndmask_b32_e32 v89, 0, v32, vcc
	v_mul_f32_e32 v32, 0x3e38aa3b, v34
	v_exp_f32_e32 v32, v32
	v_cmp_le_i32_e32 vcc, v33, v88
	v_add_u32_e32 v33, s19, v33
	s_nop 0
	v_cndmask_b32_e32 v92, 0, v32, vcc
	v_mul_f32_e32 v32, 0x3e38aa3b, v35
	v_exp_f32_e32 v32, v32
	v_cmp_le_i32_e32 vcc, v33, v88
	v_add_u32_e32 v33, s8, v33
	s_nop 0
	v_cndmask_b32_e32 v93, 0, v32, vcc
	v_mul_f32_e32 v32, 0x3e38aa3b, v36
	v_exp_f32_e32 v32, v32
	v_cmp_le_i32_e32 vcc, v33, v88
	v_add_u32_e32 v33, s19, v33
	v_cvt_pk_bf16_f32 v36, v91, v89
	s_nop 0
	v_cndmask_b32_e32 v94, 0, v32, vcc
	v_mul_f32_e32 v32, 0x3e38aa3b, v37
	v_exp_f32_e32 v32, v32
	v_cmp_le_i32_e32 vcc, v33, v88
	v_add_u32_e32 v33, s19, v33
	v_cvt_pk_bf16_f32 v37, v92, v93
	s_nop 0
	v_cndmask_b32_e32 v95, 0, v32, vcc
	v_mul_f32_e32 v32, 0x3e38aa3b, v38
	v_exp_f32_e32 v32, v32
	v_cmp_le_i32_e32 vcc, v33, v88
	v_add_u32_e32 v33, s19, v33
	v_cvt_pk_bf16_f32 v38, v94, v95
	s_nop 0
	v_cndmask_b32_e32 v96, 0, v32, vcc
	v_mul_f32_e32 v32, 0x3e38aa3b, v39
	v_exp_f32_e32 v32, v32
	v_cmp_le_i32_e32 vcc, v33, v88
	v_add_u32_e32 v33, s8, v33
	s_nop 0
	v_cndmask_b32_e32 v97, 0, v32, vcc
	v_mul_f32_e32 v32, 0x3e38aa3b, v40
	v_exp_f32_e32 v32, v32
	v_cmp_le_i32_e32 vcc, v33, v88
	v_add_u32_e32 v33, s19, v33
	v_cvt_pk_bf16_f32 v39, v96, v97
	s_nop 0
	v_cndmask_b32_e32 v40, 0, v32, vcc
	v_mul_f32_e32 v32, 0x3e38aa3b, v41
	v_exp_f32_e32 v32, v32
	v_cmp_le_i32_e32 vcc, v33, v88
	v_add_u32_e32 v33, s19, v33
	s_nop 0
	v_cndmask_b32_e32 v41, 0, v32, vcc
	v_mul_f32_e32 v32, 0x3e38aa3b, v42
	v_exp_f32_e32 v32, v32
	v_cmp_le_i32_e32 vcc, v33, v88
	v_add_u32_e32 v33, s19, v33
	s_nop 0
	v_cndmask_b32_e32 v42, 0, v32, vcc
	v_mul_f32_e32 v32, 0x3e38aa3b, v43
	v_exp_f32_e32 v32, v32
	v_cmp_le_i32_e32 vcc, v33, v88
	v_add_u32_e32 v33, s8, v33
	s_nop 0
	v_cndmask_b32_e32 v43, 0, v32, vcc
	v_mul_f32_e32 v32, 0x3e38aa3b, v44
	v_exp_f32_e32 v32, v32
	v_cmp_le_i32_e32 vcc, v33, v88
	v_add_u32_e32 v33, s19, v33
	s_nop 0
	v_cndmask_b32_e32 v44, 0, v32, vcc
	v_mul_f32_e32 v32, 0x3e38aa3b, v45
	v_exp_f32_e32 v32, v32
	v_cmp_le_i32_e32 vcc, v33, v88
	v_add_u32_e32 v33, s19, v33
	s_nop 0
	v_cndmask_b32_e32 v45, 0, v32, vcc
	v_mul_f32_e32 v32, 0x3e38aa3b, v46
	v_exp_f32_e32 v32, v32
	v_cmp_le_i32_e32 vcc, v33, v88
	v_add_u32_e32 v33, s19, v33
	v_cvt_pk_bf16_f32 v34, v44, v45
	s_nop 0
	v_cndmask_b32_e32 v46, 0, v32, vcc
	v_cmp_le_i32_e32 vcc, v33, v88
	v_add_f32_e32 v88, v90, v91
	v_add_f32_e32 v88, v89, v88
	v_mul_f32_e32 v32, 0x3e38aa3b, v47
	v_add_f32_e32 v88, v92, v88
	v_add_f32_e32 v88, v93, v88
	v_exp_f32_e32 v32, v32
	v_add_f32_e32 v88, v94, v88
	v_add_f32_e32 v88, v95, v88
	v_add_f32_e32 v88, v96, v88
	v_add_f32_e32 v88, v97, v88
	v_cndmask_b32_e32 v47, 0, v32, vcc
	v_cvt_pk_bf16_f32 v32, v40, v41
	v_add_f32_e32 v40, v40, v88
	v_add_f32_e32 v40, v41, v40
	v_add_f32_e32 v40, v42, v40
	v_add_f32_e32 v40, v43, v40
	v_add_f32_e32 v40, v44, v40
	v_add_f32_e32 v40, v45, v40
	v_cvt_pk_bf16_f32 v33, v42, v43
	v_add_f32_e32 v44, v46, v40
	ds_read2_b64 v[40:43], v87 offset0:24 offset1:26
	s_waitcnt lgkmcnt(0)
	v_mfma_f32_32x32x16_bf16 v[16:31], v[40:43], v[36:39], v[16:31]
	ds_read2_b64 v[40:43], v87 offset0:28 offset1:30
	v_cvt_pk_bf16_f32 v35, v46, v47
	s_waitcnt lgkmcnt(0)
	v_mfma_f32_32x32x16_bf16 v[16:31], v[40:43], v[32:35], v[16:31]
	ds_read2_b64 v[40:43], v86 offset0:88 offset1:90
	s_waitcnt lgkmcnt(0)
	v_mfma_f32_32x32x16_bf16 v[0:15], v[40:43], v[36:39], v[0:15]
	ds_read2_b64 v[36:39], v86 offset0:92 offset1:94
	v_add_f32_e32 v86, v47, v44
	s_waitcnt lgkmcnt(0)
	v_mfma_f32_32x32x16_bf16 v[0:15], v[36:39], v[32:35], v[0:15]
	s_add_i32 s15, s15, 1
	s_addk_i32 s17, 0x80
	s_cmp_lg_u32 s18, 4
	s_cbranch_scc0 .LBB0_482

; __device__ __forceinline__ u16 f2bf(float f) { unsigned r; asm("v_cvt_pk_bf16_f32 %0, %1, %1" : "=v"(r) : "v"(f)); return (u16)r; }
; __device__ __forceinline__ unsigned pack2(float a, float b) { unsigned r; asm("v_cvt_pk_bf16_f32 %0, %1, %2" : "=v"(r) : "v"(a), "v"(b)); return r; }
; __device__ __forceinline__ void hyena_task(const Params& p, int layer, int c, bool isctx, unsigned char* smem) {
;     ...
;           if (o == 0) {
;             uint2 ov; ov.x = pack2(r0, r1); ov.y = pack2(r2, r3);
;             *(uint2*)(YB + bb * HY_YS + t0) = ov;
;           } else {
;             u16* YS = (u16*)(p.ws + O_YS) + (rowoff + t0) * 1536 + 1024 + c;
;             YS[0] = f2bf(r0); YS[1536] = f2bf(r1); YS[2 * 1536] = f2bf(r2); YS[3 * 1536] = f2bf(r3);
;           }
.LBB0_713:
	s_or_b64 exec, exec, s[6:7]
	s_mov_b64 s[4:5], s[50:51]
	v_readlane_b32 s8, v255, 13
	s_waitcnt lgkmcnt(0)
	s_barrier
	s_load_dwordx2 s[6:7], s[4:5], 0x150
	v_readlane_b32 vcc_lo, v254, 0
	v_and_b32_e32 v1, 63, v228
	v_lshrrev_b32_e32 v2, 6, v228
	v_and_b32_e32 v3, 7, v1
	v_lshrrev_b32_e32 v4, 3, v1
	s_lshl_b32 vcc_lo, vcc_lo, 6
	v_lshl_add_u32 v5, v2, 6, v4
	v_mul_u32_u24_e32 v6, 0x9000, v5
	v_lshl_add_u32 v7, v3, 3, vcc_lo
	v_lshl_add_u32 v6, v7, 1, v6
	v_mov_b32_e32 v7, 0
	v_add_u32_e32 v12, vcc_lo, v2
	v_mul_u32_u24_e32 v12, 0xc00, v12
	v_lshl_add_u32 v12, v1, 4, v12
	v_mov_b32_e32 v13, 0
	v_mul_u32_u24_e32 v14, 0x2080, v3
	v_lshl_add_u32 v14, v5, 1, v14
	v_mul_u32_u24_e32 v15, 0x410, v2
	v_lshl_add_u32 v15, v1, 4, v15
	s_waitcnt lgkmcnt(0)
	v_mov_b32_e32 v8, s6
	v_mov_b32_e32 v9, s7
	v_lshl_add_u64 v[10:11], v[8:9], 0, v[6:7]
	v_lshl_add_u64 v[12:13], v[8:9], 0, v[12:13]
	s_mov_b64 vcc, 0xce0c000
	v_lshl_add_u64 v[10:11], v[10:11], 0, vcc
	s_mov_b64 vcc, 0x1700c800
	v_lshl_add_u64 v[12:13], v[12:13], 0, vcc
	s_mov_b64 vcc, 0x48000
	global_load_dwordx4 v[16:19], v[10:11], off
	v_lshl_add_u64 v[10:11], v[10:11], 0, vcc
	global_load_dwordx4 v[20:23], v[10:11], off
	v_lshl_add_u64 v[10:11], v[10:11], 0, vcc
	global_load_dwordx4 v[24:27], v[10:11], off
	v_lshl_add_u64 v[10:11], v[10:11], 0, vcc
	global_load_dwordx4 v[28:31], v[10:11], off
	v_lshl_add_u64 v[10:11], v[10:11], 0, vcc
	global_load_dwordx4 v[32:35], v[10:11], off
	v_lshl_add_u64 v[10:11], v[10:11], 0, vcc
	global_load_dwordx4 v[36:39], v[10:11], off
	v_lshl_add_u64 v[10:11], v[10:11], 0, vcc
	global_load_dwordx4 v[40:43], v[10:11], off
	v_lshl_add_u64 v[10:11], v[10:11], 0, vcc
	global_load_dwordx4 v[44:47], v[10:11], off
	s_waitcnt vmcnt(7)
	ds_write_b16 v14, v16 offset:0
	ds_write_b16_d16_hi v14, v16 offset:1040
	ds_write_b16 v14, v17 offset:2080
	ds_write_b16_d16_hi v14, v17 offset:3120
	ds_write_b16 v14, v18 offset:4160
	ds_write_b16_d16_hi v14, v18 offset:5200
	ds_write_b16 v14, v19 offset:6240
	ds_write_b16_d16_hi v14, v19 offset:7280
	s_waitcnt vmcnt(6)
	ds_write_b16 v14, v20 offset:16
	ds_write_b16_d16_hi v14, v20 offset:1056
	ds_write_b16 v14, v21 offset:2096
	ds_write_b16_d16_hi v14, v21 offset:3136
	ds_write_b16 v14, v22 offset:4176
	ds_write_b16_d16_hi v14, v22 offset:5216
	ds_write_b16 v14, v23 offset:6256
	ds_write_b16_d16_hi v14, v23 offset:7296
	s_waitcnt vmcnt(5)
	ds_write_b16 v14, v24 offset:32
	ds_write_b16_d16_hi v14, v24 offset:1072
	ds_write_b16 v14, v25 offset:2112
	ds_write_b16_d16_hi v14, v25 offset:3152
	ds_write_b16 v14, v26 offset:4192
	ds_write_b16_d16_hi v14, v26 offset:5232
	ds_write_b16 v14, v27 offset:6272
	ds_write_b16_d16_hi v14, v27 offset:7312
	s_waitcnt vmcnt(4)
	ds_write_b16 v14, v28 offset:48
	ds_write_b16_d16_hi v14, v28 offset:1088
	ds_write_b16 v14, v29 offset:2128
	ds_write_b16_d16_hi v14, v29 offset:3168
	ds_write_b16 v14, v30 offset:4208
	ds_write_b16_d16_hi v14, v30 offset:5248
	ds_write_b16 v14, v31 offset:6288
	ds_write_b16_d16_hi v14, v31 offset:7328
	s_waitcnt vmcnt(3)
	ds_write_b16 v14, v32 offset:64
	ds_write_b16_d16_hi v14, v32 offset:1104
	ds_write_b16 v14, v33 offset:2144
	ds_write_b16_d16_hi v14, v33 offset:3184
	ds_write_b16 v14, v34 offset:4224
	ds_write_b16_d16_hi v14, v34 offset:5264
	ds_write_b16 v14, v35 offset:6304
	ds_write_b16_d16_hi v14, v35 offset:7344
	s_waitcnt vmcnt(2)
	ds_write_b16 v14, v36 offset:80
	ds_write_b16_d16_hi v14, v36 offset:1120
	ds_write_b16 v14, v37 offset:2160
	ds_write_b16_d16_hi v14, v37 offset:3200
	ds_write_b16 v14, v38 offset:4240
	ds_write_b16_d16_hi v14, v38 offset:5280
	ds_write_b16 v14, v39 offset:6320
	ds_write_b16_d16_hi v14, v39 offset:7360
	s_waitcnt vmcnt(1)
	ds_write_b16 v14, v40 offset:96
	ds_write_b16_d16_hi v14, v40 offset:1136
	ds_write_b16 v14, v41 offset:2176
	ds_write_b16_d16_hi v14, v41 offset:3216
	ds_write_b16 v14, v42 offset:4256
	ds_write_b16_d16_hi v14, v42 offset:5296
	ds_write_b16 v14, v43 offset:6336
	ds_write_b16_d16_hi v14, v43 offset:7376
	s_waitcnt vmcnt(0)
	ds_write_b16 v14, v44 offset:112
	ds_write_b16_d16_hi v14, v44 offset:1152
	ds_write_b16 v14, v45 offset:2192
	ds_write_b16_d16_hi v14, v45 offset:3232
	ds_write_b16 v14, v46 offset:4272
	ds_write_b16_d16_hi v14, v46 offset:5312
	ds_write_b16 v14, v47 offset:6352
	ds_write_b16_d16_hi v14, v47 offset:7392
	s_waitcnt lgkmcnt(0)
	s_barrier
	s_mov_b64 vcc, 0x6000
	ds_read_b128 v[16:19], v15
	ds_read_b128 v[20:23], v15 offset:8320
	ds_read_b128 v[24:27], v15 offset:16640
	ds_read_b128 v[28:31], v15 offset:24960
	ds_read_b128 v[32:35], v15 offset:33280
	ds_read_b128 v[36:39], v15 offset:41600
	ds_read_b128 v[40:43], v15 offset:49920
	ds_read_b128 v[44:47], v15 offset:58240
	s_waitcnt lgkmcnt(7)
	global_store_dwordx4 v[12:13], v[16:19], off
	v_lshl_add_u64 v[12:13], v[12:13], 0, vcc
	s_waitcnt lgkmcnt(6)
	global_store_dwordx4 v[12:13], v[20:23], off
	v_lshl_add_u64 v[12:13], v[12:13], 0, vcc
	s_waitcnt lgkmcnt(5)
	global_store_dwordx4 v[12:13], v[24:27], off
	v_lshl_add_u64 v[12:13], v[12:13], 0, vcc
	s_waitcnt lgkmcnt(4)
	global_store_dwordx4 v[12:13], v[28:31], off
	v_lshl_add_u64 v[12:13], v[12:13], 0, vcc
	s_waitcnt lgkmcnt(3)
	global_store_dwordx4 v[12:13], v[32:35], off
	v_lshl_add_u64 v[12:13], v[12:13], 0, vcc
	s_waitcnt lgkmcnt(2)
	global_store_dwordx4 v[12:13], v[36:39], off
	v_lshl_add_u64 v[12:13], v[12:13], 0, vcc
	s_waitcnt lgkmcnt(1)
	global_store_dwordx4 v[12:13], v[40:43], off
	v_lshl_add_u64 v[12:13], v[12:13], 0, vcc
	s_waitcnt lgkmcnt(0)
	global_store_dwordx4 v[12:13], v[44:47], off
	s_barrier
; __device__ __forceinline__ int opaque_tid() { int t = threadIdx.x; asm volatile("" : "+v"(t)); return t; }
; #define PP (*get_params())
; template <int K, int lda, class Epi, class Sched>
; __device__ __forceinline__ void gemm_phase(PG8_LAS unsigned char* lds, const Sched& S, const Epi& E) {
;     const int tid = opaque_tid(), wid = __builtin_amdgcn_readfirstlane(tid >> 6), lane = tid & 63, wr = wid >> 2, wc = wid & 3, fr = lane & 15, fq = lane >> 4;
;     constexpr int nt = K / BK;
;     unsigned voffA[2], voffB[2];
; #pragma unroll
;     for (int i = 0; i < 2; ++i) { int R, C; stage_rc(tid * 16 + i * 8192, R, C); const int Rb = Epi::PERM ? ((R & ~31) + perm32(R & 31)) : R;
;         voffA[i] = (unsigned)(R * lda + C) * 2u; voffB[i] = (unsigned)(Rb * K + C) * 2u; }
;     constexpr size_t kstep = (size_t)(BK * 2);
;     constexpr size_t hstepA = (size_t)HALF * lda * 2; constexpr size_t hstepB = (size_t)HALF * K * 2;
;     const unsigned ldsw = (unsigned)wid * 1024u;
;     const int aoff = lds_byte(wr * 64 + fr, fq * 8), boff = lds_byte(wc * 32 + fr, fq * 8);
;     ...
;     Unit cur, nxt; int ui = 0;
;     if (!S.next(0, cur)) return;
;     f32x4 acc[2][2][4][2];
; #pragma unroll
;     for (int a = 0; a < 2; ++a)
; #pragma unroll
;         for (int b = 0; b < 2; ++b)
; #pragma unroll
;             for (int m = 0; m < 4; ++m)
; #pragma unroll
;                 for (int n = 0; n < 2; ++n) acc[a][b][m][n] = (f32x4){0.f, 0.f, 0.f, 0.f};
;     bf16x8 At[4][2], B0[2][2], B1[2][2];
;     const char* cA = cur.A; const char* cB0 = cur.B0;
;     PG8_STAGE(PG8_SB(0, 0), cB0, voffB); PG8_STAGE(PG8_SA(0, 0), cA, voffA); PG8_STAGE(PG8_SB(0, 1), cB0 + hstepB, voffB); PG8_STAGE(PG8_SA(0, 1), cA + hstepA, voffA);
;     if (wr == 1) PG8_BAR;
;     PG8_WAIT_V(4); PG8_BAR;
;     PG8_STAGE(PG8_SB(1, 0), cB0 + kstep, voffB); PG8_STAGE(PG8_SA(1, 0), cA + kstep, voffA); PG8_STAGE(PG8_SB(1, 1), cB0 + hstepB + kstep, voffB);
; __global__ void __launch_bounds__(512, 2) fwd_megakernel(Params p) {
;     ...
;     PH(5) {
;       const Params& q = PP;
;       pg8::SchedPlain<2> S; S.o.init(nMt, G, cblk); S.A = q.ws + O_YG; S.B = q.ws + O_WGLU + (size_t)layer * 512 * 512 * 2;
;       S.a_tile = (size_t)256 * 512 * 2; S.b_tile = (size_t)256 * 512 * 2; S.b_half = (size_t)128 * 512 * 2;
;       pg8::EpiGlu E; E.ws = q.ws; E.gb = q.in[18] + layer * 512;
;       pg8::gemm_phase<512, 512>(LDSP, S, E);
	s_mov_b32 s7, s8
	v_mov_b64_e32 v[2:3], s[4:5]
	s_mov_b32 s6, s8
	global_load_dwordx2 v[4:5], v[2:3], off offset:336
	global_load_dwordx2 v[0:1], v[2:3], off offset:336
	s_nop 0
	global_load_dwordx2 v[2:3], v[2:3], off offset:144
	s_cmp_eq_u32 s7, 0
	s_movk_i32 s4, 0x90
	s_cselect_b32 s4, s4, 0x80
	v_mov_b32_e32 v12, v228
	v_readlane_b32 s5, v254, 30
	s_cmp_lt_i32 s5, s4
	v_readfirstlane_b32 s5, v12
	s_cbranch_scc0 .LBB0_725
	s_ashr_i32 s7, s6, 31
	s_mov_b64 s[10:11], 0x1a60c000
	s_lshl_b64 s[6:7], s[6:7], 19
	s_waitcnt vmcnt(0) lgkmcnt(0)
	v_lshl_add_u64 v[136:137], v[4:5], 0, s[10:11]
	v_lshl_add_u64 v[4:5], v[4:5], 0, s[6:7]
	s_mov_b64 s[6:7], 0x898c000
	v_lshl_add_u64 v[138:139], v[4:5], 0, s[6:7]
	v_lshlrev_b32_e32 v4, 4, v12
	v_add_u32_e32 v5, 0x2000, v4
	v_ashrrev_i32_e32 v6, 31, v5
	v_lshrrev_b32_e32 v6, 22, v6
	v_add_u32_e32 v6, v5, v6
	v_ashrrev_i32_e32 v13, 10, v6
	v_mul_i32_i24_e32 v6, 0x400, v13
	v_sub_u32_e32 v5, v5, v6
	v_lshrrev_b32_e32 v6, 4, v5
	v_bitop3_b32 v5, v6, v5, 32 bitop3:0x6c
	v_ashrrev_i32_e32 v6, 31, v5
	v_lshrrev_b32_e32 v6, 26, v6
	v_add_u32_e32 v6, v5, v6
	v_lshlrev_b32_e32 v7, 3, v13
	v_ashrrev_i32_e32 v14, 6, v6
	v_and_b32_e32 v7, -16, v7
	v_add_u32_e32 v7, v14, v7
	v_and_b32_e32 v8, 3, v14
	s_mov_b32 s9, 0x3fffe0
	v_lshrrev_b32_e32 v9, 2, v7
	v_lshlrev_b32_e32 v10, 1, v7
	v_and_b32_e32 v6, 0xc0, v6
	v_and_or_b32 v8, v7, s9, v8
	v_and_b32_e32 v9, 4, v9
	v_and_b32_e32 v10, 24, v10
	v_sub_u32_e32 v5, v5, v6
	v_or3_b32 v8, v8, v9, v10
	v_lshlrev_b32_e32 v9, 5, v13
	v_ashrrev_i16_sdwa v5, v230, sext(v5) dst_sel:DWORD dst_unused:UNUSED_PAD src0_sel:DWORD src1_sel:BYTE_0
	v_and_b32_e32 v9, 32, v9
	v_bfe_i32 v15, v5, 0, 16
	v_add_lshl_u32 v5, v9, v15, 1
	v_lshl_add_u32 v140, v8, 10, v5
	v_lshl_add_u32 v142, v7, 10, v5
	v_bfe_i32 v5, v12, 27, 1
	v_lshrrev_b32_e32 v5, 22, v5
	v_add_u32_e32 v5, v4, v5
	v_and_b32_e32 v5, 0xfffffc00, v5
	v_sub_u32_e32 v4, v4, v5
	v_lshrrev_b32_e32 v5, 4, v4
	v_bitop3_b32 v5, v5, v4, 32 bitop3:0x6c
	v_ashrrev_i32_e32 v4, 31, v4
	v_lshrrev_b32_e32 v4, 26, v4
	v_add_u32_e32 v4, v5, v4
	v_ashrrev_i32_e32 v16, 6, v4
	v_ashrrev_i32_e32 v4, 31, v12
	v_lshrrev_b32_e32 v4, 26, v4
	v_add_u32_e32 v4, v12, v4
	v_ashrrev_i32_e32 v17, 6, v4
	v_lshlrev_b32_e32 v4, 3, v17
	v_and_b32_e32 v4, -16, v4
	v_add_u32_e32 v4, v16, v4
	v_and_b32_e32 v6, 3, v16
	v_lshrrev_b32_e32 v7, 2, v4
	v_lshlrev_b32_e32 v8, 1, v4
	v_and_or_b32 v6, v4, s9, v6
	v_and_b32_e32 v7, 4, v7
	v_and_b32_e32 v8, 24, v8
	v_or3_b32 v6, v6, v7, v8
	v_mul_i32_i24_e32 v8, 64, v16
	v_sub_u32_e32 v5, v5, v8
	v_readlane_b32 s14, v254, 23
	v_lshlrev_b32_e32 v7, 5, v17
	v_ashrrev_i16_sdwa v5, v230, sext(v5) dst_sel:DWORD dst_unused:UNUSED_PAD src0_sel:DWORD src1_sel:BYTE_0
	v_readlane_b32 s15, v254, 24
	v_readlane_b32 s16, v255, 9
	v_and_b32_e32 v7, 32, v7
	v_bfe_i32 v18, v5, 0, 16
	s_ashr_i32 s15, s14, 31
	v_readlane_b32 s17, v255, 10
	s_ashr_i32 s7, s5, 6
	v_add_lshl_u32 v5, v7, v18, 1
	s_lshl_b64 s[10:11], s[14:15], 18
	s_ashr_i32 s17, s16, 31
	s_lshl_b32 s28, s7, 10
	v_lshl_add_u32 v160, v6, 10, v5
	v_lshl_add_u32 v144, v4, 10, v5
	v_lshl_add_u64 v[4:5], v[136:137], 0, s[10:11]
	s_lshl_b64 s[10:11], s[16:17], 18
	v_readfirstlane_b32 s21, v5
	v_readfirstlane_b32 s20, v4
	v_lshl_add_u64 v[4:5], v[138:139], 0, s[10:11]
	s_add_i32 s29, s28, 0
	v_readfirstlane_b32 s23, v5
	v_readfirstlane_b32 s22, v4
	s_add_i32 m0, s29, 0x10000
	s_ashr_i32 s6, s5, 8
	s_add_i32 s30, s29, 0x2000
	v_mov_b32_e32 v141, v161
	v_mov_b32_e32 v145, v161
	global_load_lds_dwordx4 v160, s[22:23]
	s_add_i32 m0, s29, 0x12000
	s_add_u32 s10, s22, 0x20000
	global_load_lds_dwordx4 v140, s[22:23]
	s_mov_b32 m0, s29
	s_addc_u32 s11, s23, 0
	global_load_lds_dwordx4 v144, s[20:21]
	s_mov_b32 m0, s30
	v_mov_b32_e32 v143, v161
	global_load_lds_dwordx4 v142, s[20:21]
	s_add_i32 m0, s29, 0x14000
	v_lshl_add_u64 v[10:11], s[22:23], 0, v[160:161]
	global_load_lds_dwordx4 v160, s[10:11]
	s_add_i32 m0, s29, 0x16000
	v_lshl_add_u64 v[8:9], s[22:23], 0, v[140:141]
	global_load_lds_dwordx4 v140, s[10:11]
	s_add_u32 s10, s20, 0x20000
	s_addc_u32 s11, s21, 0
	s_add_i32 s31, s29, 0x4000
	s_mov_b32 m0, s31
	s_add_i32 s34, s29, 0x6000
	global_load_lds_dwordx4 v144, s[10:11]
	s_mov_b32 m0, s34
	v_lshl_add_u64 v[6:7], s[20:21], 0, v[144:145]
	global_load_lds_dwordx4 v142, s[10:11]
	s_cmp_lg_u32 s6, 1
	v_lshl_add_u64 v[4:5], s[20:21], 0, v[142:143]
	s_cbranch_scc1 .LBB0_716
	s_barrier

; __device__ __forceinline__ void lists_item(const Params& p, int tile, unsigned char* smem) {
;     ...
; #pragma unroll 4
;     for (int e = tid; e < 128 * 128; e += NT) {
;       int r = e >> 7, ch = e & 127;
;       const u32x4 v = *(const u32x4*)(HN + (size_t)(tile * 64 + (r >> 1)) * D + ch * 8);
;       *(u32x4*)(HNG + (size_t)sm[256 + r] * D + ch * 8) = v;
;     }
.LBB0_1095:
	v_and_b32_e32 v14, 0x3f8, v10
	v_lshlrev_b32_e32 v160, 1, v14
	v_ashrrev_i32_e32 v12, 8, v9
	v_add_u32_e32 v12, s4, v12
	v_ashrrev_i32_e32 v13, 31, v12
	v_lshlrev_b64 v[12:13], 11, v[12:13]
	v_lshl_add_u64 v[12:13], v[6:7], 0, v[12:13]
	v_lshl_add_u64 v[12:13], v[12:13], 0, v[160:161]
	global_load_dwordx4 v[32:35], v[12:13], off
	v_ashrrev_i32_e32 v16, 7, v9
	v_lshl_add_u32 v16, v16, 2, 0
	ds_read_b32 v48, v16 offset:1024
	v_add_u32_e32 v11, 0x200, v9
	v_ashrrev_i32_e32 v12, 8, v11
	v_add_u32_e32 v12, s4, v12
	v_ashrrev_i32_e32 v13, 31, v12
	v_lshlrev_b64 v[12:13], 11, v[12:13]
	v_lshl_add_u64 v[12:13], v[6:7], 0, v[12:13]
	v_lshl_add_u64 v[12:13], v[12:13], 0, v[160:161]
	global_load_dwordx4 v[36:39], v[12:13], off
	v_ashrrev_i32_e32 v16, 7, v11
	v_lshl_add_u32 v16, v16, 2, 0
	ds_read_b32 v50, v16 offset:1024
	v_add_u32_e32 v11, 0x400, v9
	v_ashrrev_i32_e32 v12, 8, v11
	v_add_u32_e32 v12, s4, v12
	v_ashrrev_i32_e32 v13, 31, v12
	v_lshlrev_b64 v[12:13], 11, v[12:13]
	v_lshl_add_u64 v[12:13], v[6:7], 0, v[12:13]
	v_lshl_add_u64 v[12:13], v[12:13], 0, v[160:161]
	global_load_dwordx4 v[40:43], v[12:13], off
	v_ashrrev_i32_e32 v16, 7, v11
	v_lshl_add_u32 v16, v16, 2, 0
	ds_read_b32 v52, v16 offset:1024
	v_add_u32_e32 v11, 0x600, v9
	v_ashrrev_i32_e32 v12, 8, v11
	v_add_u32_e32 v12, s4, v12
	v_ashrrev_i32_e32 v13, 31, v12
	v_lshlrev_b64 v[12:13], 11, v[12:13]
	v_lshl_add_u64 v[12:13], v[6:7], 0, v[12:13]
	v_lshl_add_u64 v[12:13], v[12:13], 0, v[160:161]
	global_load_dwordx4 v[44:47], v[12:13], off
	v_ashrrev_i32_e32 v16, 7, v11
	v_lshl_add_u32 v16, v16, 2, 0
	ds_read_b32 v54, v16 offset:1024
	s_movk_i32 s5, 0x37ff
	v_cmp_lt_i32_e32 vcc, s5, v9
	v_add_u32_e32 v10, 0x4000, v10
	s_or_b64 s[10:11], vcc, s[10:11]
	v_add_u32_e32 v9, 0x800, v9
	s_waitcnt lgkmcnt(0)
	v_ashrrev_i32_e32 v49, 31, v48
	v_lshlrev_b64 v[48:49], 11, v[48:49]
	v_lshl_add_u64 v[48:49], v[4:5], 0, v[48:49]
	v_lshl_add_u64 v[48:49], v[48:49], 0, v[160:161]
	v_ashrrev_i32_e32 v51, 31, v50
	v_lshlrev_b64 v[50:51], 11, v[50:51]
	v_lshl_add_u64 v[50:51], v[4:5], 0, v[50:51]
	v_lshl_add_u64 v[50:51], v[50:51], 0, v[160:161]
	v_ashrrev_i32_e32 v53, 31, v52
	v_lshlrev_b64 v[52:53], 11, v[52:53]
	v_lshl_add_u64 v[52:53], v[4:5], 0, v[52:53]
	v_lshl_add_u64 v[52:53], v[52:53], 0, v[160:161]
	v_ashrrev_i32_e32 v55, 31, v54
	v_lshlrev_b64 v[54:55], 11, v[54:55]
	v_lshl_add_u64 v[54:55], v[4:5], 0, v[54:55]
	v_lshl_add_u64 v[54:55], v[54:55], 0, v[160:161]
	s_waitcnt vmcnt(3)
	global_store_dwordx4 v[48:49], v[32:35], off
	s_waitcnt vmcnt(3)
	global_store_dwordx4 v[50:51], v[36:39], off
	s_waitcnt vmcnt(3)
	global_store_dwordx4 v[52:53], v[40:43], off
	s_waitcnt vmcnt(3)
	global_store_dwordx4 v[54:55], v[44:47], off
	s_andn2_b64 exec, exec, s[10:11]
	s_cbranch_execnz .LBB0_1095
